# K-loops: scalar/address work after an MFMA cluster moved behind the barrier it signals
# baseline (speedup 1.0000x reference)
.Lkprio_0:
.LBB0_243:
	s_cmpk_eq_i32 s4, 0x700
	v_lshl_add_u64 v[170:171], v[152:153], 0, s[4:5]
	s_mov_b64 s[6:7], 0x4280100
	v_lshl_add_u64 v[170:171], v[170:171], 0, s[6:7]
	s_cselect_b64 vcc, -1, 0
	s_add_i32 s6, 0, 0x10000
	v_cndmask_b32_e32 v245, v171, v147, vcc
	v_add_u32_e32 v171, s6, v174
	ds_read_b128 v[176:179], v171
	ds_read_b128 v[180:183], v171 offset:1024
	ds_read_b128 v[184:187], v171 offset:2048
	ds_read_b128 v[188:191], v171 offset:3072
	v_cndmask_b32_e32 v244, v170, v146, vcc
	v_lshl_add_u64 v[170:171], v[168:169], 0, s[4:5]
	v_cndmask_b32_e32 v171, v171, v145, vcc
	v_cndmask_b32_e32 v170, v170, v144, vcc
	v_lshl_add_u64 v[228:229], v[148:149], 0, s[4:5]
	s_add_i32 m0, s26, 0xc000
	ds_read_b128 v[192:195], v175
	ds_read_b128 v[196:199], v175 offset:1024
	ds_read_b128 v[200:203], v175 offset:2048
	ds_read_b128 v[204:207], v175 offset:3072
	ds_read_b128 v[210:213], v175 offset:4096
	ds_read_b128 v[214:217], v175 offset:5120
	ds_read_b128 v[218:221], v175 offset:6144
	ds_read_b128 v[222:225], v175 offset:7168
	global_load_lds_dwordx4 v[228:229], off
	v_lshl_add_u64 v[228:229], v[150:151], 0, s[4:5]
	s_add_i32 m0, s26, 0xe000
	s_nop 0
	global_load_lds_dwordx4 v[228:229], off
	s_waitcnt lgkmcnt(8)
	s_barrier
	s_waitcnt lgkmcnt(7)
	v_mfma_f32_16x16x32_bf16 v[126:129], v[176:179], v[192:195], v[126:129]
	v_mfma_f32_16x16x32_bf16 v[122:125], v[184:187], v[192:195], v[122:125]
	s_waitcnt lgkmcnt(5)
	v_mfma_f32_16x16x32_bf16 v[118:121], v[176:179], v[200:203], v[118:121]
	v_mfma_f32_16x16x32_bf16 v[114:117], v[184:187], v[200:203], v[114:117]
	s_waitcnt lgkmcnt(3)
	v_mfma_f32_16x16x32_bf16 v[110:113], v[176:179], v[210:213], v[110:113]
	v_mfma_f32_16x16x32_bf16 v[106:109], v[184:187], v[210:213], v[106:109]
	s_waitcnt lgkmcnt(1)
	v_mfma_f32_16x16x32_bf16 v[102:105], v[176:179], v[218:221], v[102:105]
	v_mfma_f32_16x16x32_bf16 v[98:101], v[184:187], v[218:221], v[98:101]
	v_mfma_f32_16x16x32_bf16 v[126:129], v[180:183], v[196:199], v[126:129]
	v_mfma_f32_16x16x32_bf16 v[122:125], v[188:191], v[196:199], v[122:125]
	v_mfma_f32_16x16x32_bf16 v[118:121], v[180:183], v[204:207], v[118:121]
	v_mfma_f32_16x16x32_bf16 v[114:117], v[188:191], v[204:207], v[114:117]
	v_mfma_f32_16x16x32_bf16 v[110:113], v[180:183], v[214:217], v[110:113]
	v_mfma_f32_16x16x32_bf16 v[106:109], v[188:191], v[214:217], v[106:109]
	s_waitcnt lgkmcnt(0)
	v_mfma_f32_16x16x32_bf16 v[102:105], v[180:183], v[222:225], v[102:105]
	v_mfma_f32_16x16x32_bf16 v[98:101], v[188:191], v[222:225], v[98:101]
	s_barrier
	s_add_i32 s7, 0, 0x14000
	s_add_i32 s6, s6, s13
	v_add_u32_e32 v208, s7, v174
	v_lshl_add_u64 v[246:247], v[170:171], 0, v[132:133]
	s_mov_b32 m0, s6
	ds_read_b128 v[228:231], v208
	ds_read_b128 v[232:235], v208 offset:1024
	ds_read_b128 v[236:239], v208 offset:2048
	ds_read_b128 v[240:243], v208 offset:3072
	global_load_lds_dwordx4 v[246:247], off
	v_lshl_add_u64 v[248:249], v[170:171], 0, v[142:143]
	s_add_i32 m0, s6, 0x2000
	s_nop 0
	global_load_lds_dwordx4 v[248:249], off
	s_barrier
	s_waitcnt lgkmcnt(3)
	v_mfma_f32_16x16x32_bf16 v[94:97], v[228:231], v[192:195], v[94:97]
	s_waitcnt lgkmcnt(1)
	v_mfma_f32_16x16x32_bf16 v[90:93], v[236:239], v[192:195], v[90:93]
	v_mfma_f32_16x16x32_bf16 v[86:89], v[228:231], v[200:203], v[86:89]
	v_mfma_f32_16x16x32_bf16 v[82:85], v[236:239], v[200:203], v[82:85]
	v_mfma_f32_16x16x32_bf16 v[78:81], v[228:231], v[210:213], v[78:81]
	v_mfma_f32_16x16x32_bf16 v[74:77], v[236:239], v[210:213], v[74:77]
	v_mfma_f32_16x16x32_bf16 v[70:73], v[228:231], v[218:221], v[70:73]
	v_mfma_f32_16x16x32_bf16 v[66:69], v[236:239], v[218:221], v[66:69]
	v_mfma_f32_16x16x32_bf16 v[94:97], v[232:235], v[196:199], v[94:97]
	s_waitcnt lgkmcnt(0)
	v_mfma_f32_16x16x32_bf16 v[90:93], v[240:243], v[196:199], v[90:93]
	v_mfma_f32_16x16x32_bf16 v[86:89], v[232:235], v[204:207], v[86:89]
	v_mfma_f32_16x16x32_bf16 v[82:85], v[240:243], v[204:207], v[82:85]
	v_mfma_f32_16x16x32_bf16 v[78:81], v[232:235], v[214:217], v[78:81]
	v_mfma_f32_16x16x32_bf16 v[74:77], v[240:243], v[214:217], v[74:77]
	v_mfma_f32_16x16x32_bf16 v[70:73], v[232:235], v[222:225], v[70:73]
	v_mfma_f32_16x16x32_bf16 v[66:69], v[240:243], v[222:225], v[66:69]
	s_barrier
	s_mov_b32 m0, s26
	v_lshl_add_u64 v[250:251], v[244:245], 0, v[132:133]
	ds_read_b128 v[192:195], v175 offset:16384
	ds_read_b128 v[196:199], v175 offset:17408
	ds_read_b128 v[200:203], v175 offset:18432
	ds_read_b128 v[204:207], v175 offset:19456
	ds_read_b128 v[210:213], v175 offset:20480
	ds_read_b128 v[214:217], v175 offset:21504
	ds_read_b128 v[218:221], v175 offset:22528
	ds_read_b128 v[222:225], v175 offset:23552
	global_load_lds_dwordx4 v[250:251], off
	v_lshl_add_u64 v[252:253], v[244:245], 0, v[142:143]
	s_mov_b32 m0, s41
	s_nop 0
	global_load_lds_dwordx4 v[252:253], off
	s_barrier
	s_waitcnt lgkmcnt(7)
	v_mfma_f32_16x16x32_bf16 v[62:65], v[176:179], v[192:195], v[62:65]
	v_mfma_f32_16x16x32_bf16 v[58:61], v[184:187], v[192:195], v[58:61]
	s_waitcnt lgkmcnt(5)
	v_mfma_f32_16x16x32_bf16 v[54:57], v[176:179], v[200:203], v[54:57]
	v_mfma_f32_16x16x32_bf16 v[50:53], v[184:187], v[200:203], v[50:53]
	s_waitcnt lgkmcnt(3)
	v_mfma_f32_16x16x32_bf16 v[46:49], v[176:179], v[210:213], v[46:49]
	v_mfma_f32_16x16x32_bf16 v[42:45], v[184:187], v[210:213], v[42:45]
	s_waitcnt lgkmcnt(1)
	v_mfma_f32_16x16x32_bf16 v[38:41], v[176:179], v[218:221], v[38:41]
	v_mfma_f32_16x16x32_bf16 v[34:37], v[184:187], v[218:221], v[34:37]
	v_mfma_f32_16x16x32_bf16 v[62:65], v[180:183], v[196:199], v[62:65]
	v_mfma_f32_16x16x32_bf16 v[58:61], v[188:191], v[196:199], v[58:61]
	v_mfma_f32_16x16x32_bf16 v[54:57], v[180:183], v[204:207], v[54:57]
	v_mfma_f32_16x16x32_bf16 v[50:53], v[188:191], v[204:207], v[50:53]
	v_mfma_f32_16x16x32_bf16 v[46:49], v[180:183], v[214:217], v[46:49]
	v_mfma_f32_16x16x32_bf16 v[42:45], v[188:191], v[214:217], v[42:45]
	s_waitcnt lgkmcnt(0)
	v_mfma_f32_16x16x32_bf16 v[38:41], v[180:183], v[222:225], v[38:41]
	v_mfma_f32_16x16x32_bf16 v[34:37], v[188:191], v[222:225], v[34:37]
	s_barrier
	v_lshl_add_u64 v[176:177], v[170:171], 0, s[28:29]
	s_add_i32 s6, s7, s13
	v_lshl_add_u64 v[178:179], v[176:177], 0, v[132:133]
	s_mov_b32 m0, s6
	v_lshl_add_u64 v[176:177], v[176:177], 0, v[142:143]
	global_load_lds_dwordx4 v[178:179], off
	s_add_i32 m0, s6, 0x2000
	s_nop 0
	global_load_lds_dwordx4 v[176:177], off
	s_waitcnt vmcnt(6)
	s_barrier
	v_mfma_f32_16x16x32_bf16 v[30:33], v[228:231], v[192:195], v[30:33]
	v_mfma_f32_16x16x32_bf16 v[26:29], v[236:239], v[192:195], v[26:29]
	v_mfma_f32_16x16x32_bf16 v[22:25], v[228:231], v[200:203], v[22:25]
	v_mfma_f32_16x16x32_bf16 v[18:21], v[236:239], v[200:203], v[18:21]
	v_mfma_f32_16x16x32_bf16 v[14:17], v[228:231], v[210:213], v[14:17]
	v_mfma_f32_16x16x32_bf16 v[10:13], v[236:239], v[210:213], v[10:13]
	v_mfma_f32_16x16x32_bf16 v[6:9], v[228:231], v[218:221], v[6:9]
	v_mfma_f32_16x16x32_bf16 v[2:5], v[236:239], v[218:221], v[2:5]
	v_mfma_f32_16x16x32_bf16 v[30:33], v[232:235], v[196:199], v[30:33]
	v_mfma_f32_16x16x32_bf16 v[26:29], v[240:243], v[196:199], v[26:29]
	v_mfma_f32_16x16x32_bf16 v[22:25], v[232:235], v[204:207], v[22:25]
	v_mfma_f32_16x16x32_bf16 v[18:21], v[240:243], v[204:207], v[18:21]
	v_mfma_f32_16x16x32_bf16 v[14:17], v[232:235], v[214:217], v[14:17]
	v_mfma_f32_16x16x32_bf16 v[10:13], v[240:243], v[214:217], v[10:13]
	v_mfma_f32_16x16x32_bf16 v[6:9], v[232:235], v[222:225], v[6:9]
	v_mfma_f32_16x16x32_bf16 v[2:5], v[240:243], v[222:225], v[2:5]
	s_barrier
	s_add_i32 s6, 0, 0x18000
	v_add_u32_e32 v188, s6, v174
	ds_read_b128 v[176:179], v188
	ds_read_b128 v[180:183], v188 offset:1024
	ds_read_b128 v[184:187], v188 offset:2048
	ds_read_b128 v[188:191], v188 offset:3072
	v_lshl_add_u64 v[228:229], v[244:245], 0, s[28:29]
	s_mov_b32 m0, s42
	v_lshl_add_u64 v[230:231], v[228:229], 0, v[132:133]
	ds_read_b128 v[192:195], v175 offset:32768
	ds_read_b128 v[196:199], v175 offset:33792
	ds_read_b128 v[200:203], v175 offset:34816
	ds_read_b128 v[204:207], v175 offset:35840
	ds_read_b128 v[210:213], v175 offset:36864
	ds_read_b128 v[214:217], v175 offset:37888
	ds_read_b128 v[218:221], v175 offset:38912
	ds_read_b128 v[222:225], v175 offset:39936
	global_load_lds_dwordx4 v[230:231], off
	v_lshl_add_u64 v[228:229], v[228:229], 0, v[142:143]
	s_mov_b32 m0, s43
	s_nop 0
	global_load_lds_dwordx4 v[228:229], off
	s_waitcnt lgkmcnt(8)
	s_barrier
	s_waitcnt lgkmcnt(7)
	v_mfma_f32_16x16x32_bf16 v[126:129], v[176:179], v[192:195], v[126:129]
	v_mfma_f32_16x16x32_bf16 v[122:125], v[184:187], v[192:195], v[122:125]
	s_waitcnt lgkmcnt(5)
	v_mfma_f32_16x16x32_bf16 v[118:121], v[176:179], v[200:203], v[118:121]
	v_mfma_f32_16x16x32_bf16 v[114:117], v[184:187], v[200:203], v[114:117]
	s_waitcnt lgkmcnt(3)
	v_mfma_f32_16x16x32_bf16 v[110:113], v[176:179], v[210:213], v[110:113]
	v_mfma_f32_16x16x32_bf16 v[106:109], v[184:187], v[210:213], v[106:109]
	s_waitcnt lgkmcnt(1)
	v_mfma_f32_16x16x32_bf16 v[102:105], v[176:179], v[218:221], v[102:105]
	v_mfma_f32_16x16x32_bf16 v[98:101], v[184:187], v[218:221], v[98:101]
	v_mfma_f32_16x16x32_bf16 v[126:129], v[180:183], v[196:199], v[126:129]
	v_mfma_f32_16x16x32_bf16 v[122:125], v[188:191], v[196:199], v[122:125]
	v_mfma_f32_16x16x32_bf16 v[118:121], v[180:183], v[204:207], v[118:121]
	v_mfma_f32_16x16x32_bf16 v[114:117], v[188:191], v[204:207], v[114:117]
	v_mfma_f32_16x16x32_bf16 v[110:113], v[180:183], v[214:217], v[110:113]
	v_mfma_f32_16x16x32_bf16 v[106:109], v[188:191], v[214:217], v[106:109]
	s_waitcnt lgkmcnt(0)
	v_mfma_f32_16x16x32_bf16 v[102:105], v[180:183], v[222:225], v[102:105]
	v_mfma_f32_16x16x32_bf16 v[98:101], v[188:191], v[222:225], v[98:101]
	s_barrier
	s_add_i32 s7, 0, 0x1c000
	s_add_i32 s6, s6, s13
	v_add_u32_e32 v208, s7, v174
	v_lshl_add_u64 v[244:245], v[246:247], 0, s[30:31]
	s_mov_b32 m0, s6
	ds_read_b128 v[228:231], v208
	ds_read_b128 v[232:235], v208 offset:1024
	ds_read_b128 v[236:239], v208 offset:2048
	ds_read_b128 v[240:243], v208 offset:3072
	global_load_lds_dwordx4 v[244:245], off
	v_lshl_add_u64 v[244:245], v[248:249], 0, s[30:31]
	s_add_i32 m0, s6, 0x2000
	s_nop 0
	global_load_lds_dwordx4 v[244:245], off
	s_barrier
	s_waitcnt lgkmcnt(3)
	v_mfma_f32_16x16x32_bf16 v[94:97], v[228:231], v[192:195], v[94:97]
	s_waitcnt lgkmcnt(1)
	v_mfma_f32_16x16x32_bf16 v[90:93], v[236:239], v[192:195], v[90:93]
	v_mfma_f32_16x16x32_bf16 v[86:89], v[228:231], v[200:203], v[86:89]
	v_mfma_f32_16x16x32_bf16 v[82:85], v[236:239], v[200:203], v[82:85]
	v_mfma_f32_16x16x32_bf16 v[78:81], v[228:231], v[210:213], v[78:81]
	v_mfma_f32_16x16x32_bf16 v[74:77], v[236:239], v[210:213], v[74:77]
	v_mfma_f32_16x16x32_bf16 v[70:73], v[228:231], v[218:221], v[70:73]
	v_mfma_f32_16x16x32_bf16 v[66:69], v[236:239], v[218:221], v[66:69]
	v_mfma_f32_16x16x32_bf16 v[94:97], v[232:235], v[196:199], v[94:97]
	s_waitcnt lgkmcnt(0)
	v_mfma_f32_16x16x32_bf16 v[90:93], v[240:243], v[196:199], v[90:93]
	v_mfma_f32_16x16x32_bf16 v[86:89], v[232:235], v[204:207], v[86:89]
	v_mfma_f32_16x16x32_bf16 v[82:85], v[240:243], v[204:207], v[82:85]
	v_mfma_f32_16x16x32_bf16 v[78:81], v[232:235], v[214:217], v[78:81]
	v_mfma_f32_16x16x32_bf16 v[74:77], v[240:243], v[214:217], v[74:77]
	v_mfma_f32_16x16x32_bf16 v[70:73], v[232:235], v[222:225], v[70:73]
	v_mfma_f32_16x16x32_bf16 v[66:69], v[240:243], v[222:225], v[66:69]
	s_barrier
	s_mov_b32 m0, s44
	v_lshl_add_u64 v[244:245], v[250:251], 0, s[30:31]
	ds_read_b128 v[192:195], v175 offset:49152
	ds_read_b128 v[196:199], v175 offset:50176
	ds_read_b128 v[200:203], v175 offset:51200
	ds_read_b128 v[204:207], v175 offset:52224
	ds_read_b128 v[210:213], v175 offset:53248
	ds_read_b128 v[214:217], v175 offset:54272
	ds_read_b128 v[218:221], v175 offset:55296
	ds_read_b128 v[222:225], v175 offset:56320
	global_load_lds_dwordx4 v[244:245], off
	v_lshl_add_u64 v[244:245], v[252:253], 0, s[30:31]
	s_mov_b32 m0, s45
	s_nop 0
	global_load_lds_dwordx4 v[244:245], off
	s_barrier
	s_waitcnt lgkmcnt(7)
	v_mfma_f32_16x16x32_bf16 v[62:65], v[176:179], v[192:195], v[62:65]
	v_mfma_f32_16x16x32_bf16 v[58:61], v[184:187], v[192:195], v[58:61]
	s_waitcnt lgkmcnt(5)
	v_mfma_f32_16x16x32_bf16 v[54:57], v[176:179], v[200:203], v[54:57]
	v_mfma_f32_16x16x32_bf16 v[50:53], v[184:187], v[200:203], v[50:53]
	s_waitcnt lgkmcnt(3)
	v_mfma_f32_16x16x32_bf16 v[46:49], v[176:179], v[210:213], v[46:49]
	v_mfma_f32_16x16x32_bf16 v[42:45], v[184:187], v[210:213], v[42:45]
	s_waitcnt lgkmcnt(1)
	v_mfma_f32_16x16x32_bf16 v[38:41], v[176:179], v[218:221], v[38:41]
	v_mfma_f32_16x16x32_bf16 v[34:37], v[184:187], v[218:221], v[34:37]
	v_mfma_f32_16x16x32_bf16 v[62:65], v[180:183], v[196:199], v[62:65]
	v_mfma_f32_16x16x32_bf16 v[58:61], v[188:191], v[196:199], v[58:61]
	v_mfma_f32_16x16x32_bf16 v[54:57], v[180:183], v[204:207], v[54:57]
	v_mfma_f32_16x16x32_bf16 v[50:53], v[188:191], v[204:207], v[50:53]
	v_mfma_f32_16x16x32_bf16 v[46:49], v[180:183], v[214:217], v[46:49]
	v_mfma_f32_16x16x32_bf16 v[42:45], v[188:191], v[214:217], v[42:45]
	s_waitcnt lgkmcnt(0)
	v_mfma_f32_16x16x32_bf16 v[38:41], v[180:183], v[222:225], v[38:41]
	v_mfma_f32_16x16x32_bf16 v[34:37], v[188:191], v[222:225], v[34:37]
	s_barrier
	v_lshl_add_u64 v[170:171], v[170:171], 0, s[34:35]
	s_add_i32 s6, s7, s13
	v_lshl_add_u64 v[176:177], v[170:171], 0, v[132:133]
	s_mov_b32 m0, s6
	v_lshl_add_u64 v[170:171], v[170:171], 0, v[142:143]
	global_load_lds_dwordx4 v[176:177], off
	s_add_i32 m0, s6, 0x2000
	s_nop 0
	global_load_lds_dwordx4 v[170:171], off
	s_waitcnt vmcnt(6)
	s_barrier
	v_mfma_f32_16x16x32_bf16 v[30:33], v[228:231], v[192:195], v[30:33]
	v_mfma_f32_16x16x32_bf16 v[26:29], v[236:239], v[192:195], v[26:29]
	v_mfma_f32_16x16x32_bf16 v[22:25], v[228:231], v[200:203], v[22:25]
	v_mfma_f32_16x16x32_bf16 v[18:21], v[236:239], v[200:203], v[18:21]
	v_mfma_f32_16x16x32_bf16 v[14:17], v[228:231], v[210:213], v[14:17]
	v_mfma_f32_16x16x32_bf16 v[10:13], v[236:239], v[210:213], v[10:13]
	v_mfma_f32_16x16x32_bf16 v[6:9], v[228:231], v[218:221], v[6:9]
	v_mfma_f32_16x16x32_bf16 v[2:5], v[236:239], v[218:221], v[2:5]
	v_mfma_f32_16x16x32_bf16 v[30:33], v[232:235], v[196:199], v[30:33]
	v_mfma_f32_16x16x32_bf16 v[26:29], v[240:243], v[196:199], v[26:29]
	v_mfma_f32_16x16x32_bf16 v[22:25], v[232:235], v[204:207], v[22:25]
	v_mfma_f32_16x16x32_bf16 v[18:21], v[240:243], v[204:207], v[18:21]
	v_mfma_f32_16x16x32_bf16 v[14:17], v[232:235], v[214:217], v[14:17]
	v_mfma_f32_16x16x32_bf16 v[10:13], v[240:243], v[214:217], v[10:13]
	v_mfma_f32_16x16x32_bf16 v[6:9], v[232:235], v[222:225], v[6:9]
	v_mfma_f32_16x16x32_bf16 v[2:5], v[240:243], v[222:225], v[2:5]
	s_barrier
	s_add_i32 s46, s46, 2
	s_add_u32 s4, s4, 0x100
	s_addc_u32 s5, s5, 0
	s_cmp_lt_u32 s46, 14
	s_cbranch_scc1 .LBB0_243
	s_setprio 0
	s_waitcnt vmcnt(0)
	s_cmpk_gt_u32 s12, 0xff
	s_cbranch_scc1 .LBB0_246
	s_barrier

.Lkprio_1:
.LBB0_756:
	s_add_u32 s42, s6, 0xfbd20080
	s_addc_u32 s43, s7, -1
	s_cmp_lg_u32 s41, 20
	s_cselect_b32 s43, s43, 0
	s_cselect_b32 s42, s42, 0
	s_add_i32 s44, 0, 0x10000
	v_add_u32_e32 v152, s44, v168
	ds_read_b128 v[170:173], v152
	ds_read_b128 v[174:177], v152 offset:1024
	ds_read_b128 v[178:181], v152 offset:2048
	ds_read_b128 v[182:185], v152 offset:3072
	v_lshl_add_u64 v[206:207], v[146:147], 0, s[42:43]
	v_lshl_add_u64 v[152:153], v[144:145], 0, s[42:43]
	v_lshl_add_u64 v[222:223], v[148:149], 0, s[6:7]
	s_add_i32 m0, s34, 0xc000
	ds_read_b128 v[186:189], v169
	ds_read_b128 v[190:193], v169 offset:1024
	ds_read_b128 v[194:197], v169 offset:2048
	ds_read_b128 v[198:201], v169 offset:3072
	ds_read_b128 v[202:205], v169 offset:4096
	ds_read_b128 v[210:213], v169 offset:5120
	ds_read_b128 v[214:217], v169 offset:6144
	ds_read_b128 v[218:221], v169 offset:7168
	global_load_lds_dwordx4 v[222:223], off
	v_lshl_add_u64 v[222:223], v[150:151], 0, s[6:7]
	s_add_i32 m0, s34, 0xe000
	s_nop 0
	global_load_lds_dwordx4 v[222:223], off
	s_waitcnt lgkmcnt(8)
	s_barrier
	s_waitcnt lgkmcnt(7)
	v_mfma_f32_16x16x32_bf16 v[126:129], v[170:173], v[186:189], v[126:129]
	v_mfma_f32_16x16x32_bf16 v[122:125], v[178:181], v[186:189], v[122:125]
	s_waitcnt lgkmcnt(5)
	v_mfma_f32_16x16x32_bf16 v[118:121], v[170:173], v[194:197], v[118:121]
	v_mfma_f32_16x16x32_bf16 v[114:117], v[178:181], v[194:197], v[114:117]
	s_waitcnt lgkmcnt(3)
	v_mfma_f32_16x16x32_bf16 v[110:113], v[170:173], v[202:205], v[110:113]
	v_mfma_f32_16x16x32_bf16 v[106:109], v[178:181], v[202:205], v[106:109]
	s_waitcnt lgkmcnt(1)
	v_mfma_f32_16x16x32_bf16 v[102:105], v[170:173], v[214:217], v[102:105]
	v_mfma_f32_16x16x32_bf16 v[98:101], v[178:181], v[214:217], v[98:101]
	v_mfma_f32_16x16x32_bf16 v[126:129], v[174:177], v[190:193], v[126:129]
	v_mfma_f32_16x16x32_bf16 v[122:125], v[182:185], v[190:193], v[122:125]
	v_mfma_f32_16x16x32_bf16 v[118:121], v[174:177], v[198:201], v[118:121]
	v_mfma_f32_16x16x32_bf16 v[114:117], v[182:185], v[198:201], v[114:117]
	v_mfma_f32_16x16x32_bf16 v[110:113], v[174:177], v[210:213], v[110:113]
	v_mfma_f32_16x16x32_bf16 v[106:109], v[182:185], v[210:213], v[106:109]
	s_waitcnt lgkmcnt(0)
	v_mfma_f32_16x16x32_bf16 v[102:105], v[174:177], v[218:221], v[102:105]
	v_mfma_f32_16x16x32_bf16 v[98:101], v[182:185], v[218:221], v[98:101]
	s_barrier
	s_add_i32 s42, 0, 0x14000
	s_add_i32 s43, s44, s33
	v_add_u32_e32 v208, s42, v168
	v_lshl_add_u64 v[240:241], v[152:153], 0, v[134:135]
	s_mov_b32 m0, s43
	ds_read_b128 v[222:225], v208
	ds_read_b128 v[228:231], v208 offset:1024
	ds_read_b128 v[232:235], v208 offset:2048
	ds_read_b128 v[236:239], v208 offset:3072
	global_load_lds_dwordx4 v[240:241], off
	v_lshl_add_u64 v[242:243], v[152:153], 0, v[142:143]
	s_add_i32 m0, s43, 0x2000
	s_nop 0
	global_load_lds_dwordx4 v[242:243], off
	s_barrier
	s_waitcnt lgkmcnt(3)
	v_mfma_f32_16x16x32_bf16 v[94:97], v[222:225], v[186:189], v[94:97]
	s_waitcnt lgkmcnt(1)
	v_mfma_f32_16x16x32_bf16 v[90:93], v[232:235], v[186:189], v[90:93]
	v_mfma_f32_16x16x32_bf16 v[86:89], v[222:225], v[194:197], v[86:89]
	v_mfma_f32_16x16x32_bf16 v[82:85], v[232:235], v[194:197], v[82:85]
	v_mfma_f32_16x16x32_bf16 v[78:81], v[222:225], v[202:205], v[78:81]
	v_mfma_f32_16x16x32_bf16 v[74:77], v[232:235], v[202:205], v[74:77]
	v_mfma_f32_16x16x32_bf16 v[70:73], v[222:225], v[214:217], v[70:73]
	v_mfma_f32_16x16x32_bf16 v[66:69], v[232:235], v[214:217], v[66:69]
	v_mfma_f32_16x16x32_bf16 v[94:97], v[228:231], v[190:193], v[94:97]
	s_waitcnt lgkmcnt(0)
	v_mfma_f32_16x16x32_bf16 v[90:93], v[236:239], v[190:193], v[90:93]
	v_mfma_f32_16x16x32_bf16 v[86:89], v[228:231], v[198:201], v[86:89]
	v_mfma_f32_16x16x32_bf16 v[82:85], v[236:239], v[198:201], v[82:85]
	v_mfma_f32_16x16x32_bf16 v[78:81], v[228:231], v[210:213], v[78:81]
	v_mfma_f32_16x16x32_bf16 v[74:77], v[236:239], v[210:213], v[74:77]
	v_mfma_f32_16x16x32_bf16 v[70:73], v[228:231], v[218:221], v[70:73]
	v_mfma_f32_16x16x32_bf16 v[66:69], v[236:239], v[218:221], v[66:69]
	s_barrier
	s_mov_b32 m0, s34
	v_lshl_add_u64 v[244:245], v[206:207], 0, v[134:135]
	ds_read_b128 v[186:189], v169 offset:16384
	ds_read_b128 v[190:193], v169 offset:17408
	ds_read_b128 v[194:197], v169 offset:18432
	ds_read_b128 v[198:201], v169 offset:19456
	ds_read_b128 v[202:205], v169 offset:20480
	ds_read_b128 v[210:213], v169 offset:21504
	ds_read_b128 v[214:217], v169 offset:22528
	ds_read_b128 v[218:221], v169 offset:23552
	global_load_lds_dwordx4 v[244:245], off
	v_lshl_add_u64 v[246:247], v[206:207], 0, v[142:143]
	s_mov_b32 m0, s35
	s_nop 0
	global_load_lds_dwordx4 v[246:247], off
	s_barrier
	s_waitcnt lgkmcnt(7)
	v_mfma_f32_16x16x32_bf16 v[62:65], v[170:173], v[186:189], v[62:65]
	v_mfma_f32_16x16x32_bf16 v[58:61], v[178:181], v[186:189], v[58:61]
	s_waitcnt lgkmcnt(5)
	v_mfma_f32_16x16x32_bf16 v[54:57], v[170:173], v[194:197], v[54:57]
	v_mfma_f32_16x16x32_bf16 v[50:53], v[178:181], v[194:197], v[50:53]
	s_waitcnt lgkmcnt(3)
	v_mfma_f32_16x16x32_bf16 v[46:49], v[170:173], v[202:205], v[46:49]
	v_mfma_f32_16x16x32_bf16 v[42:45], v[178:181], v[202:205], v[42:45]
	s_waitcnt lgkmcnt(1)
	v_mfma_f32_16x16x32_bf16 v[38:41], v[170:173], v[214:217], v[38:41]
	v_mfma_f32_16x16x32_bf16 v[34:37], v[178:181], v[214:217], v[34:37]
	v_mfma_f32_16x16x32_bf16 v[62:65], v[174:177], v[190:193], v[62:65]
	v_mfma_f32_16x16x32_bf16 v[58:61], v[182:185], v[190:193], v[58:61]
	v_mfma_f32_16x16x32_bf16 v[54:57], v[174:177], v[198:201], v[54:57]
	v_mfma_f32_16x16x32_bf16 v[50:53], v[182:185], v[198:201], v[50:53]
	v_mfma_f32_16x16x32_bf16 v[46:49], v[174:177], v[210:213], v[46:49]
	v_mfma_f32_16x16x32_bf16 v[42:45], v[182:185], v[210:213], v[42:45]
	s_waitcnt lgkmcnt(0)
	v_mfma_f32_16x16x32_bf16 v[38:41], v[174:177], v[218:221], v[38:41]
	v_mfma_f32_16x16x32_bf16 v[34:37], v[182:185], v[218:221], v[34:37]
	s_barrier
	v_lshl_add_u64 v[170:171], v[152:153], 0, s[14:15]
	s_add_i32 s42, s42, s33
	v_lshl_add_u64 v[172:173], v[170:171], 0, v[134:135]
	s_mov_b32 m0, s42
	v_lshl_add_u64 v[170:171], v[170:171], 0, v[142:143]
	global_load_lds_dwordx4 v[172:173], off
	s_add_i32 m0, s42, 0x2000
	s_nop 0
	global_load_lds_dwordx4 v[170:171], off
	s_waitcnt vmcnt(6)
	s_barrier
	v_mfma_f32_16x16x32_bf16 v[30:33], v[222:225], v[186:189], v[30:33]
	v_mfma_f32_16x16x32_bf16 v[26:29], v[232:235], v[186:189], v[26:29]
	v_mfma_f32_16x16x32_bf16 v[22:25], v[222:225], v[194:197], v[22:25]
	v_mfma_f32_16x16x32_bf16 v[18:21], v[232:235], v[194:197], v[18:21]
	v_mfma_f32_16x16x32_bf16 v[14:17], v[222:225], v[202:205], v[14:17]
	v_mfma_f32_16x16x32_bf16 v[10:13], v[232:235], v[202:205], v[10:13]
	v_mfma_f32_16x16x32_bf16 v[6:9], v[222:225], v[214:217], v[6:9]
	v_mfma_f32_16x16x32_bf16 v[2:5], v[232:235], v[214:217], v[2:5]
	v_mfma_f32_16x16x32_bf16 v[30:33], v[228:231], v[190:193], v[30:33]
	v_mfma_f32_16x16x32_bf16 v[26:29], v[236:239], v[190:193], v[26:29]
	v_mfma_f32_16x16x32_bf16 v[22:25], v[228:231], v[198:201], v[22:25]
	v_mfma_f32_16x16x32_bf16 v[18:21], v[236:239], v[198:201], v[18:21]
	v_mfma_f32_16x16x32_bf16 v[14:17], v[228:231], v[210:213], v[14:17]
	v_mfma_f32_16x16x32_bf16 v[10:13], v[236:239], v[210:213], v[10:13]
	v_mfma_f32_16x16x32_bf16 v[6:9], v[228:231], v[218:221], v[6:9]
	v_mfma_f32_16x16x32_bf16 v[2:5], v[236:239], v[218:221], v[2:5]
	s_barrier
	s_add_i32 s42, 0, 0x18000
	v_add_u32_e32 v182, s42, v168
	ds_read_b128 v[170:173], v182
	ds_read_b128 v[174:177], v182 offset:1024
	ds_read_b128 v[178:181], v182 offset:2048
	ds_read_b128 v[182:185], v182 offset:3072
	v_lshl_add_u64 v[206:207], v[206:207], 0, s[14:15]
	s_mov_b32 m0, s37
	v_lshl_add_u64 v[222:223], v[206:207], 0, v[134:135]
	ds_read_b128 v[186:189], v169 offset:32768
	ds_read_b128 v[190:193], v169 offset:33792
	ds_read_b128 v[194:197], v169 offset:34816
	ds_read_b128 v[198:201], v169 offset:35840
	ds_read_b128 v[202:205], v169 offset:36864
	ds_read_b128 v[210:213], v169 offset:37888
	ds_read_b128 v[214:217], v169 offset:38912
	ds_read_b128 v[218:221], v169 offset:39936
	global_load_lds_dwordx4 v[222:223], off
	v_lshl_add_u64 v[206:207], v[206:207], 0, v[142:143]
	s_mov_b32 m0, s38
	s_nop 0
	global_load_lds_dwordx4 v[206:207], off
	s_waitcnt lgkmcnt(8)
	s_barrier
	s_waitcnt lgkmcnt(7)
	v_mfma_f32_16x16x32_bf16 v[126:129], v[170:173], v[186:189], v[126:129]
	v_mfma_f32_16x16x32_bf16 v[122:125], v[178:181], v[186:189], v[122:125]
	s_waitcnt lgkmcnt(5)
	v_mfma_f32_16x16x32_bf16 v[118:121], v[170:173], v[194:197], v[118:121]
	v_mfma_f32_16x16x32_bf16 v[114:117], v[178:181], v[194:197], v[114:117]
	s_waitcnt lgkmcnt(3)
	v_mfma_f32_16x16x32_bf16 v[110:113], v[170:173], v[202:205], v[110:113]
	v_mfma_f32_16x16x32_bf16 v[106:109], v[178:181], v[202:205], v[106:109]
	s_waitcnt lgkmcnt(1)
	v_mfma_f32_16x16x32_bf16 v[102:105], v[170:173], v[214:217], v[102:105]
	v_mfma_f32_16x16x32_bf16 v[98:101], v[178:181], v[214:217], v[98:101]
	v_mfma_f32_16x16x32_bf16 v[126:129], v[174:177], v[190:193], v[126:129]
	v_mfma_f32_16x16x32_bf16 v[122:125], v[182:185], v[190:193], v[122:125]
	v_mfma_f32_16x16x32_bf16 v[118:121], v[174:177], v[198:201], v[118:121]
	v_mfma_f32_16x16x32_bf16 v[114:117], v[182:185], v[198:201], v[114:117]
	v_mfma_f32_16x16x32_bf16 v[110:113], v[174:177], v[210:213], v[110:113]
	v_mfma_f32_16x16x32_bf16 v[106:109], v[182:185], v[210:213], v[106:109]
	s_waitcnt lgkmcnt(0)
	v_mfma_f32_16x16x32_bf16 v[102:105], v[174:177], v[218:221], v[102:105]
	v_mfma_f32_16x16x32_bf16 v[98:101], v[182:185], v[218:221], v[98:101]
	s_barrier
	s_add_i32 s43, 0, 0x1c000
	v_add_u32_e32 v206, s43, v168
	s_add_i32 s42, s42, s33
	ds_read_b128 v[222:225], v206
	ds_read_b128 v[228:231], v206 offset:1024
	ds_read_b128 v[232:235], v206 offset:2048
	ds_read_b128 v[236:239], v206 offset:3072
	v_lshl_add_u64 v[206:207], v[240:241], 0, s[16:17]
	s_mov_b32 m0, s42
	s_nop 0
	global_load_lds_dwordx4 v[206:207], off
	v_lshl_add_u64 v[206:207], v[242:243], 0, s[16:17]
	s_add_i32 m0, s42, 0x2000
	s_nop 0
	global_load_lds_dwordx4 v[206:207], off
	s_barrier
	s_waitcnt lgkmcnt(3)
	v_mfma_f32_16x16x32_bf16 v[94:97], v[222:225], v[186:189], v[94:97]
	s_waitcnt lgkmcnt(1)
	v_mfma_f32_16x16x32_bf16 v[90:93], v[232:235], v[186:189], v[90:93]
	v_mfma_f32_16x16x32_bf16 v[86:89], v[222:225], v[194:197], v[86:89]
	v_mfma_f32_16x16x32_bf16 v[82:85], v[232:235], v[194:197], v[82:85]
	v_mfma_f32_16x16x32_bf16 v[78:81], v[222:225], v[202:205], v[78:81]
	v_mfma_f32_16x16x32_bf16 v[74:77], v[232:235], v[202:205], v[74:77]
	v_mfma_f32_16x16x32_bf16 v[70:73], v[222:225], v[214:217], v[70:73]
	v_mfma_f32_16x16x32_bf16 v[66:69], v[232:235], v[214:217], v[66:69]
	v_mfma_f32_16x16x32_bf16 v[94:97], v[228:231], v[190:193], v[94:97]
	s_waitcnt lgkmcnt(0)
	v_mfma_f32_16x16x32_bf16 v[90:93], v[236:239], v[190:193], v[90:93]
	v_mfma_f32_16x16x32_bf16 v[86:89], v[228:231], v[198:201], v[86:89]
	v_mfma_f32_16x16x32_bf16 v[82:85], v[236:239], v[198:201], v[82:85]
	v_mfma_f32_16x16x32_bf16 v[78:81], v[228:231], v[210:213], v[78:81]
	v_mfma_f32_16x16x32_bf16 v[74:77], v[236:239], v[210:213], v[74:77]
	v_mfma_f32_16x16x32_bf16 v[70:73], v[228:231], v[218:221], v[70:73]
	v_mfma_f32_16x16x32_bf16 v[66:69], v[236:239], v[218:221], v[66:69]
	s_barrier
	s_mov_b32 m0, s39
	v_lshl_add_u64 v[206:207], v[244:245], 0, s[16:17]
	ds_read_b128 v[186:189], v169 offset:49152
	ds_read_b128 v[190:193], v169 offset:50176
	ds_read_b128 v[194:197], v169 offset:51200
	ds_read_b128 v[198:201], v169 offset:52224
	ds_read_b128 v[202:205], v169 offset:53248
	ds_read_b128 v[210:213], v169 offset:54272
	ds_read_b128 v[214:217], v169 offset:55296
	ds_read_b128 v[218:221], v169 offset:56320
	global_load_lds_dwordx4 v[206:207], off
	v_lshl_add_u64 v[206:207], v[246:247], 0, s[16:17]
	s_mov_b32 m0, s40
	s_nop 0
	global_load_lds_dwordx4 v[206:207], off
	s_barrier
	s_waitcnt lgkmcnt(7)
	v_mfma_f32_16x16x32_bf16 v[62:65], v[170:173], v[186:189], v[62:65]
	v_mfma_f32_16x16x32_bf16 v[58:61], v[178:181], v[186:189], v[58:61]
	s_waitcnt lgkmcnt(5)
	v_mfma_f32_16x16x32_bf16 v[54:57], v[170:173], v[194:197], v[54:57]
	v_mfma_f32_16x16x32_bf16 v[50:53], v[178:181], v[194:197], v[50:53]
	s_waitcnt lgkmcnt(3)
	v_mfma_f32_16x16x32_bf16 v[46:49], v[170:173], v[202:205], v[46:49]
	v_mfma_f32_16x16x32_bf16 v[42:45], v[178:181], v[202:205], v[42:45]
	s_waitcnt lgkmcnt(1)
	v_mfma_f32_16x16x32_bf16 v[38:41], v[170:173], v[214:217], v[38:41]
	v_mfma_f32_16x16x32_bf16 v[34:37], v[178:181], v[214:217], v[34:37]
	v_mfma_f32_16x16x32_bf16 v[62:65], v[174:177], v[190:193], v[62:65]
	v_mfma_f32_16x16x32_bf16 v[58:61], v[182:185], v[190:193], v[58:61]
	v_mfma_f32_16x16x32_bf16 v[54:57], v[174:177], v[198:201], v[54:57]
	v_mfma_f32_16x16x32_bf16 v[50:53], v[182:185], v[198:201], v[50:53]
	v_mfma_f32_16x16x32_bf16 v[46:49], v[174:177], v[210:213], v[46:49]
	v_mfma_f32_16x16x32_bf16 v[42:45], v[182:185], v[210:213], v[42:45]
	s_waitcnt lgkmcnt(0)
	v_mfma_f32_16x16x32_bf16 v[38:41], v[174:177], v[218:221], v[38:41]
	v_mfma_f32_16x16x32_bf16 v[34:37], v[182:185], v[218:221], v[34:37]
	s_barrier
	v_lshl_add_u64 v[152:153], v[152:153], 0, s[18:19]
	s_add_i32 s42, s43, s33
	v_lshl_add_u64 v[170:171], v[152:153], 0, v[134:135]
	s_mov_b32 m0, s42
	v_lshl_add_u64 v[152:153], v[152:153], 0, v[142:143]
	global_load_lds_dwordx4 v[170:171], off
	s_add_i32 m0, s42, 0x2000
	s_nop 0
	global_load_lds_dwordx4 v[152:153], off
	s_waitcnt vmcnt(6)
	s_barrier
	v_mfma_f32_16x16x32_bf16 v[30:33], v[222:225], v[186:189], v[30:33]
	v_mfma_f32_16x16x32_bf16 v[26:29], v[232:235], v[186:189], v[26:29]
	v_mfma_f32_16x16x32_bf16 v[22:25], v[222:225], v[194:197], v[22:25]
	v_mfma_f32_16x16x32_bf16 v[18:21], v[232:235], v[194:197], v[18:21]
	v_mfma_f32_16x16x32_bf16 v[14:17], v[222:225], v[202:205], v[14:17]
	v_mfma_f32_16x16x32_bf16 v[10:13], v[232:235], v[202:205], v[10:13]
	v_mfma_f32_16x16x32_bf16 v[6:9], v[222:225], v[214:217], v[6:9]
	v_mfma_f32_16x16x32_bf16 v[2:5], v[232:235], v[214:217], v[2:5]
	v_mfma_f32_16x16x32_bf16 v[30:33], v[228:231], v[190:193], v[30:33]
	v_mfma_f32_16x16x32_bf16 v[26:29], v[236:239], v[190:193], v[26:29]
	v_mfma_f32_16x16x32_bf16 v[22:25], v[228:231], v[198:201], v[22:25]
	v_mfma_f32_16x16x32_bf16 v[18:21], v[236:239], v[198:201], v[18:21]
	v_mfma_f32_16x16x32_bf16 v[14:17], v[228:231], v[210:213], v[14:17]
	v_mfma_f32_16x16x32_bf16 v[10:13], v[236:239], v[210:213], v[10:13]
	v_mfma_f32_16x16x32_bf16 v[6:9], v[228:231], v[218:221], v[6:9]
	v_mfma_f32_16x16x32_bf16 v[2:5], v[236:239], v[218:221], v[2:5]
	s_barrier
	s_add_i32 s41, s41, 2
	s_add_u32 s6, s6, 0x100
	s_addc_u32 s7, s7, 0
	s_cmp_lt_u32 s41, 22
	s_cbranch_scc1 .LBB0_756
	s_setprio 0
	s_waitcnt vmcnt(0)
	s_cmpk_gt_u32 s31, 0xff
	s_cbranch_scc1 .LBB0_759
	s_barrier

.Lkprio_2:
.LBB0_914:
	s_cmpk_eq_i32 s6, 0x700
	v_lshl_add_u64 v[170:171], v[150:151], 0, s[6:7]
	v_lshl_add_u64 v[170:171], v[170:171], 0, s[20:21]
	s_cselect_b64 vcc, -1, 0
	s_add_i32 s9, 0, 0x10000
	v_cndmask_b32_e32 v245, v171, v149, vcc
	v_add_u32_e32 v171, s9, v173
	ds_read_b128 v[176:179], v171
	ds_read_b128 v[180:183], v171 offset:1024
	ds_read_b128 v[184:187], v171 offset:2048
	ds_read_b128 v[188:191], v171 offset:3072
	v_cndmask_b32_e32 v244, v170, v148, vcc
	v_lshl_add_u64 v[170:171], v[168:169], 0, s[6:7]
	v_cndmask_b32_e32 v171, v171, v147, vcc
	v_cndmask_b32_e32 v170, v170, v146, vcc
	v_lshl_add_u64 v[228:229], v[152:153], 0, s[6:7]
	s_add_i32 m0, s34, 0xc000
	ds_read_b128 v[192:195], v174
	ds_read_b128 v[196:199], v174 offset:1024
	ds_read_b128 v[200:203], v174 offset:2048
	ds_read_b128 v[204:207], v174 offset:3072
	ds_read_b128 v[210:213], v174 offset:4096
	ds_read_b128 v[214:217], v174 offset:5120
	ds_read_b128 v[218:221], v174 offset:6144
	ds_read_b128 v[222:225], v174 offset:7168
	global_load_lds_dwordx4 v[228:229], off
	v_lshl_add_u64 v[228:229], v[166:167], 0, s[6:7]
	s_add_i32 m0, s34, 0xe000
	s_nop 0
	global_load_lds_dwordx4 v[228:229], off
	s_waitcnt lgkmcnt(8)
	s_barrier
	s_waitcnt lgkmcnt(7)
	v_mfma_f32_16x16x32_bf16 v[126:129], v[176:179], v[192:195], v[126:129]
	v_mfma_f32_16x16x32_bf16 v[122:125], v[184:187], v[192:195], v[122:125]
	s_waitcnt lgkmcnt(5)
	v_mfma_f32_16x16x32_bf16 v[118:121], v[176:179], v[200:203], v[118:121]
	v_mfma_f32_16x16x32_bf16 v[114:117], v[184:187], v[200:203], v[114:117]
	s_waitcnt lgkmcnt(3)
	v_mfma_f32_16x16x32_bf16 v[110:113], v[176:179], v[210:213], v[110:113]
	v_mfma_f32_16x16x32_bf16 v[106:109], v[184:187], v[210:213], v[106:109]
	s_waitcnt lgkmcnt(1)
	v_mfma_f32_16x16x32_bf16 v[102:105], v[176:179], v[218:221], v[102:105]
	v_mfma_f32_16x16x32_bf16 v[98:101], v[184:187], v[218:221], v[98:101]
	v_mfma_f32_16x16x32_bf16 v[126:129], v[180:183], v[196:199], v[126:129]
	v_mfma_f32_16x16x32_bf16 v[122:125], v[188:191], v[196:199], v[122:125]
	v_mfma_f32_16x16x32_bf16 v[118:121], v[180:183], v[204:207], v[118:121]
	v_mfma_f32_16x16x32_bf16 v[114:117], v[188:191], v[204:207], v[114:117]
	v_mfma_f32_16x16x32_bf16 v[110:113], v[180:183], v[214:217], v[110:113]
	v_mfma_f32_16x16x32_bf16 v[106:109], v[188:191], v[214:217], v[106:109]
	s_waitcnt lgkmcnt(0)
	v_mfma_f32_16x16x32_bf16 v[102:105], v[180:183], v[222:225], v[102:105]
	v_mfma_f32_16x16x32_bf16 v[98:101], v[188:191], v[222:225], v[98:101]
	s_barrier
	s_add_i32 s57, 0, 0x14000
	s_add_i32 s9, s9, s39
	v_add_u32_e32 v175, s57, v173
	v_lshl_add_u64 v[246:247], v[170:171], 0, v[134:135]
	s_mov_b32 m0, s9
	ds_read_b128 v[228:231], v175
	ds_read_b128 v[232:235], v175 offset:1024
	ds_read_b128 v[236:239], v175 offset:2048
	ds_read_b128 v[240:243], v175 offset:3072
	global_load_lds_dwordx4 v[246:247], off
	v_lshl_add_u64 v[248:249], v[170:171], 0, v[144:145]
	s_add_i32 m0, s9, 0x2000
	s_nop 0
	global_load_lds_dwordx4 v[248:249], off
	s_barrier
	s_waitcnt lgkmcnt(3)
	v_mfma_f32_16x16x32_bf16 v[94:97], v[228:231], v[192:195], v[94:97]
	s_waitcnt lgkmcnt(1)
	v_mfma_f32_16x16x32_bf16 v[90:93], v[236:239], v[192:195], v[90:93]
	v_mfma_f32_16x16x32_bf16 v[86:89], v[228:231], v[200:203], v[86:89]
	v_mfma_f32_16x16x32_bf16 v[82:85], v[236:239], v[200:203], v[82:85]
	v_mfma_f32_16x16x32_bf16 v[78:81], v[228:231], v[210:213], v[78:81]
	v_mfma_f32_16x16x32_bf16 v[74:77], v[236:239], v[210:213], v[74:77]
	v_mfma_f32_16x16x32_bf16 v[70:73], v[228:231], v[218:221], v[70:73]
	v_mfma_f32_16x16x32_bf16 v[66:69], v[236:239], v[218:221], v[66:69]
	v_mfma_f32_16x16x32_bf16 v[94:97], v[232:235], v[196:199], v[94:97]
	s_waitcnt lgkmcnt(0)
	v_mfma_f32_16x16x32_bf16 v[90:93], v[240:243], v[196:199], v[90:93]
	v_mfma_f32_16x16x32_bf16 v[86:89], v[232:235], v[204:207], v[86:89]
	v_mfma_f32_16x16x32_bf16 v[82:85], v[240:243], v[204:207], v[82:85]
	v_mfma_f32_16x16x32_bf16 v[78:81], v[232:235], v[214:217], v[78:81]
	v_mfma_f32_16x16x32_bf16 v[74:77], v[240:243], v[214:217], v[74:77]
	v_mfma_f32_16x16x32_bf16 v[70:73], v[232:235], v[222:225], v[70:73]
	v_mfma_f32_16x16x32_bf16 v[66:69], v[240:243], v[222:225], v[66:69]
	s_barrier
	s_mov_b32 m0, s34
	v_lshl_add_u64 v[250:251], v[244:245], 0, v[134:135]
	ds_read_b128 v[192:195], v174 offset:16384
	ds_read_b128 v[196:199], v174 offset:17408
	ds_read_b128 v[200:203], v174 offset:18432
	ds_read_b128 v[204:207], v174 offset:19456
	ds_read_b128 v[210:213], v174 offset:20480
	ds_read_b128 v[214:217], v174 offset:21504
	ds_read_b128 v[218:221], v174 offset:22528
	ds_read_b128 v[222:225], v174 offset:23552
	global_load_lds_dwordx4 v[250:251], off
	v_lshl_add_u64 v[252:253], v[244:245], 0, v[144:145]
	s_mov_b32 m0, s41
	s_nop 0
	global_load_lds_dwordx4 v[252:253], off
	s_barrier
	s_waitcnt lgkmcnt(7)
	v_mfma_f32_16x16x32_bf16 v[62:65], v[176:179], v[192:195], v[62:65]
	v_mfma_f32_16x16x32_bf16 v[58:61], v[184:187], v[192:195], v[58:61]
	s_waitcnt lgkmcnt(5)
	v_mfma_f32_16x16x32_bf16 v[54:57], v[176:179], v[200:203], v[54:57]
	v_mfma_f32_16x16x32_bf16 v[50:53], v[184:187], v[200:203], v[50:53]
	s_waitcnt lgkmcnt(3)
	v_mfma_f32_16x16x32_bf16 v[46:49], v[176:179], v[210:213], v[46:49]
	v_mfma_f32_16x16x32_bf16 v[42:45], v[184:187], v[210:213], v[42:45]
	s_waitcnt lgkmcnt(1)
	v_mfma_f32_16x16x32_bf16 v[38:41], v[176:179], v[218:221], v[38:41]
	v_mfma_f32_16x16x32_bf16 v[34:37], v[184:187], v[218:221], v[34:37]
	v_mfma_f32_16x16x32_bf16 v[62:65], v[180:183], v[196:199], v[62:65]
	v_mfma_f32_16x16x32_bf16 v[58:61], v[188:191], v[196:199], v[58:61]
	v_mfma_f32_16x16x32_bf16 v[54:57], v[180:183], v[204:207], v[54:57]
	v_mfma_f32_16x16x32_bf16 v[50:53], v[188:191], v[204:207], v[50:53]
	v_mfma_f32_16x16x32_bf16 v[46:49], v[180:183], v[214:217], v[46:49]
	v_mfma_f32_16x16x32_bf16 v[42:45], v[188:191], v[214:217], v[42:45]
	s_waitcnt lgkmcnt(0)
	v_mfma_f32_16x16x32_bf16 v[38:41], v[180:183], v[222:225], v[38:41]
	v_mfma_f32_16x16x32_bf16 v[34:37], v[188:191], v[222:225], v[34:37]
	s_barrier
	v_lshl_add_u64 v[176:177], v[170:171], 0, s[10:11]
	s_add_i32 s9, s57, s39
	v_lshl_add_u64 v[178:179], v[176:177], 0, v[134:135]
	s_mov_b32 m0, s9
	v_lshl_add_u64 v[176:177], v[176:177], 0, v[144:145]
	global_load_lds_dwordx4 v[178:179], off
	s_add_i32 m0, s9, 0x2000
	s_nop 0
	global_load_lds_dwordx4 v[176:177], off
	s_waitcnt vmcnt(6)
	s_barrier
	v_mfma_f32_16x16x32_bf16 v[30:33], v[228:231], v[192:195], v[30:33]
	v_mfma_f32_16x16x32_bf16 v[26:29], v[236:239], v[192:195], v[26:29]
	v_mfma_f32_16x16x32_bf16 v[22:25], v[228:231], v[200:203], v[22:25]
	v_mfma_f32_16x16x32_bf16 v[18:21], v[236:239], v[200:203], v[18:21]
	v_mfma_f32_16x16x32_bf16 v[14:17], v[228:231], v[210:213], v[14:17]
	v_mfma_f32_16x16x32_bf16 v[10:13], v[236:239], v[210:213], v[10:13]
	v_mfma_f32_16x16x32_bf16 v[6:9], v[228:231], v[218:221], v[6:9]
	v_mfma_f32_16x16x32_bf16 v[2:5], v[236:239], v[218:221], v[2:5]
	v_mfma_f32_16x16x32_bf16 v[30:33], v[232:235], v[196:199], v[30:33]
	v_mfma_f32_16x16x32_bf16 v[26:29], v[240:243], v[196:199], v[26:29]
	v_mfma_f32_16x16x32_bf16 v[22:25], v[232:235], v[204:207], v[22:25]
	v_mfma_f32_16x16x32_bf16 v[18:21], v[240:243], v[204:207], v[18:21]
	v_mfma_f32_16x16x32_bf16 v[14:17], v[232:235], v[214:217], v[14:17]
	v_mfma_f32_16x16x32_bf16 v[10:13], v[240:243], v[214:217], v[10:13]
	v_mfma_f32_16x16x32_bf16 v[6:9], v[232:235], v[222:225], v[6:9]
	v_mfma_f32_16x16x32_bf16 v[2:5], v[240:243], v[222:225], v[2:5]
	s_barrier
	s_add_i32 s9, 0, 0x18000
	v_add_u32_e32 v175, s9, v173
	ds_read_b128 v[176:179], v175
	ds_read_b128 v[180:183], v175 offset:1024
	ds_read_b128 v[184:187], v175 offset:2048
	ds_read_b128 v[188:191], v175 offset:3072
	v_lshl_add_u64 v[228:229], v[244:245], 0, s[10:11]
	s_mov_b32 m0, s42
	v_lshl_add_u64 v[230:231], v[228:229], 0, v[134:135]
	ds_read_b128 v[192:195], v174 offset:32768
	ds_read_b128 v[196:199], v174 offset:33792
	ds_read_b128 v[200:203], v174 offset:34816
	ds_read_b128 v[204:207], v174 offset:35840
	ds_read_b128 v[210:213], v174 offset:36864
	ds_read_b128 v[214:217], v174 offset:37888
	ds_read_b128 v[218:221], v174 offset:38912
	ds_read_b128 v[222:225], v174 offset:39936
	global_load_lds_dwordx4 v[230:231], off
	v_lshl_add_u64 v[228:229], v[228:229], 0, v[144:145]
	s_mov_b32 m0, s43
	s_nop 0
	global_load_lds_dwordx4 v[228:229], off
	s_waitcnt lgkmcnt(8)
	s_barrier
	s_waitcnt lgkmcnt(7)
	v_mfma_f32_16x16x32_bf16 v[126:129], v[176:179], v[192:195], v[126:129]
	v_mfma_f32_16x16x32_bf16 v[122:125], v[184:187], v[192:195], v[122:125]
	s_waitcnt lgkmcnt(5)
	v_mfma_f32_16x16x32_bf16 v[118:121], v[176:179], v[200:203], v[118:121]
	v_mfma_f32_16x16x32_bf16 v[114:117], v[184:187], v[200:203], v[114:117]
	s_waitcnt lgkmcnt(3)
	v_mfma_f32_16x16x32_bf16 v[110:113], v[176:179], v[210:213], v[110:113]
	v_mfma_f32_16x16x32_bf16 v[106:109], v[184:187], v[210:213], v[106:109]
	s_waitcnt lgkmcnt(1)
	v_mfma_f32_16x16x32_bf16 v[102:105], v[176:179], v[218:221], v[102:105]
	v_mfma_f32_16x16x32_bf16 v[98:101], v[184:187], v[218:221], v[98:101]
	v_mfma_f32_16x16x32_bf16 v[126:129], v[180:183], v[196:199], v[126:129]
	v_mfma_f32_16x16x32_bf16 v[122:125], v[188:191], v[196:199], v[122:125]
	v_mfma_f32_16x16x32_bf16 v[118:121], v[180:183], v[204:207], v[118:121]
	v_mfma_f32_16x16x32_bf16 v[114:117], v[188:191], v[204:207], v[114:117]
	v_mfma_f32_16x16x32_bf16 v[110:113], v[180:183], v[214:217], v[110:113]
	v_mfma_f32_16x16x32_bf16 v[106:109], v[188:191], v[214:217], v[106:109]
	s_waitcnt lgkmcnt(0)
	v_mfma_f32_16x16x32_bf16 v[102:105], v[180:183], v[222:225], v[102:105]
	v_mfma_f32_16x16x32_bf16 v[98:101], v[188:191], v[222:225], v[98:101]
	s_barrier
	s_add_i32 s57, 0, 0x1c000
	s_add_i32 s9, s9, s39
	v_add_u32_e32 v175, s57, v173
	v_lshl_add_u64 v[244:245], v[246:247], 0, s[16:17]
	s_mov_b32 m0, s9
	ds_read_b128 v[228:231], v175
	ds_read_b128 v[232:235], v175 offset:1024
	ds_read_b128 v[236:239], v175 offset:2048
	ds_read_b128 v[240:243], v175 offset:3072
	global_load_lds_dwordx4 v[244:245], off
	v_lshl_add_u64 v[244:245], v[248:249], 0, s[16:17]
	s_add_i32 m0, s9, 0x2000
	s_nop 0
	global_load_lds_dwordx4 v[244:245], off
	s_barrier
	s_waitcnt lgkmcnt(3)
	v_mfma_f32_16x16x32_bf16 v[94:97], v[228:231], v[192:195], v[94:97]
	s_waitcnt lgkmcnt(1)
	v_mfma_f32_16x16x32_bf16 v[90:93], v[236:239], v[192:195], v[90:93]
	v_mfma_f32_16x16x32_bf16 v[86:89], v[228:231], v[200:203], v[86:89]
	v_mfma_f32_16x16x32_bf16 v[82:85], v[236:239], v[200:203], v[82:85]
	v_mfma_f32_16x16x32_bf16 v[78:81], v[228:231], v[210:213], v[78:81]
	v_mfma_f32_16x16x32_bf16 v[74:77], v[236:239], v[210:213], v[74:77]
	v_mfma_f32_16x16x32_bf16 v[70:73], v[228:231], v[218:221], v[70:73]
	v_mfma_f32_16x16x32_bf16 v[66:69], v[236:239], v[218:221], v[66:69]
	v_mfma_f32_16x16x32_bf16 v[94:97], v[232:235], v[196:199], v[94:97]
	s_waitcnt lgkmcnt(0)
	v_mfma_f32_16x16x32_bf16 v[90:93], v[240:243], v[196:199], v[90:93]
	v_mfma_f32_16x16x32_bf16 v[86:89], v[232:235], v[204:207], v[86:89]
	v_mfma_f32_16x16x32_bf16 v[82:85], v[240:243], v[204:207], v[82:85]
	v_mfma_f32_16x16x32_bf16 v[78:81], v[232:235], v[214:217], v[78:81]
	v_mfma_f32_16x16x32_bf16 v[74:77], v[240:243], v[214:217], v[74:77]
	v_mfma_f32_16x16x32_bf16 v[70:73], v[232:235], v[222:225], v[70:73]
	v_mfma_f32_16x16x32_bf16 v[66:69], v[240:243], v[222:225], v[66:69]
	s_barrier
	s_mov_b32 m0, s55
	v_lshl_add_u64 v[244:245], v[250:251], 0, s[16:17]
	ds_read_b128 v[192:195], v174 offset:49152
	ds_read_b128 v[196:199], v174 offset:50176
	ds_read_b128 v[200:203], v174 offset:51200
	ds_read_b128 v[204:207], v174 offset:52224
	ds_read_b128 v[210:213], v174 offset:53248
	ds_read_b128 v[214:217], v174 offset:54272
	ds_read_b128 v[218:221], v174 offset:55296
	ds_read_b128 v[222:225], v174 offset:56320
	global_load_lds_dwordx4 v[244:245], off
	v_lshl_add_u64 v[244:245], v[252:253], 0, s[16:17]
	s_mov_b32 m0, s56
	s_nop 0
	global_load_lds_dwordx4 v[244:245], off
	s_barrier
	s_waitcnt lgkmcnt(7)
	v_mfma_f32_16x16x32_bf16 v[62:65], v[176:179], v[192:195], v[62:65]
	v_mfma_f32_16x16x32_bf16 v[58:61], v[184:187], v[192:195], v[58:61]
	s_waitcnt lgkmcnt(5)
	v_mfma_f32_16x16x32_bf16 v[54:57], v[176:179], v[200:203], v[54:57]
	v_mfma_f32_16x16x32_bf16 v[50:53], v[184:187], v[200:203], v[50:53]
	s_waitcnt lgkmcnt(3)
	v_mfma_f32_16x16x32_bf16 v[46:49], v[176:179], v[210:213], v[46:49]
	v_mfma_f32_16x16x32_bf16 v[42:45], v[184:187], v[210:213], v[42:45]
	s_waitcnt lgkmcnt(1)
	v_mfma_f32_16x16x32_bf16 v[38:41], v[176:179], v[218:221], v[38:41]
	v_mfma_f32_16x16x32_bf16 v[34:37], v[184:187], v[218:221], v[34:37]
	v_mfma_f32_16x16x32_bf16 v[62:65], v[180:183], v[196:199], v[62:65]
	v_mfma_f32_16x16x32_bf16 v[58:61], v[188:191], v[196:199], v[58:61]
	v_mfma_f32_16x16x32_bf16 v[54:57], v[180:183], v[204:207], v[54:57]
	v_mfma_f32_16x16x32_bf16 v[50:53], v[188:191], v[204:207], v[50:53]
	v_mfma_f32_16x16x32_bf16 v[46:49], v[180:183], v[214:217], v[46:49]
	v_mfma_f32_16x16x32_bf16 v[42:45], v[188:191], v[214:217], v[42:45]
	s_waitcnt lgkmcnt(0)
	v_mfma_f32_16x16x32_bf16 v[38:41], v[180:183], v[222:225], v[38:41]
	v_mfma_f32_16x16x32_bf16 v[34:37], v[188:191], v[222:225], v[34:37]
	s_barrier
	v_lshl_add_u64 v[170:171], v[170:171], 0, s[18:19]
	s_add_i32 s9, s57, s39
	v_lshl_add_u64 v[176:177], v[170:171], 0, v[134:135]
	s_mov_b32 m0, s9
	v_lshl_add_u64 v[170:171], v[170:171], 0, v[144:145]
	global_load_lds_dwordx4 v[176:177], off
	s_add_i32 m0, s9, 0x2000
	s_nop 0
	global_load_lds_dwordx4 v[170:171], off
	s_waitcnt vmcnt(6)
	s_barrier
	v_mfma_f32_16x16x32_bf16 v[30:33], v[228:231], v[192:195], v[30:33]
	v_mfma_f32_16x16x32_bf16 v[26:29], v[236:239], v[192:195], v[26:29]
	v_mfma_f32_16x16x32_bf16 v[22:25], v[228:231], v[200:203], v[22:25]
	v_mfma_f32_16x16x32_bf16 v[18:21], v[236:239], v[200:203], v[18:21]
	v_mfma_f32_16x16x32_bf16 v[14:17], v[228:231], v[210:213], v[14:17]
	v_mfma_f32_16x16x32_bf16 v[10:13], v[236:239], v[210:213], v[10:13]
	v_mfma_f32_16x16x32_bf16 v[6:9], v[228:231], v[218:221], v[6:9]
	v_mfma_f32_16x16x32_bf16 v[2:5], v[236:239], v[218:221], v[2:5]
	v_mfma_f32_16x16x32_bf16 v[30:33], v[232:235], v[196:199], v[30:33]
	v_mfma_f32_16x16x32_bf16 v[26:29], v[240:243], v[196:199], v[26:29]
	v_mfma_f32_16x16x32_bf16 v[22:25], v[232:235], v[204:207], v[22:25]
	v_mfma_f32_16x16x32_bf16 v[18:21], v[240:243], v[204:207], v[18:21]
	v_mfma_f32_16x16x32_bf16 v[14:17], v[232:235], v[214:217], v[14:17]
	v_mfma_f32_16x16x32_bf16 v[10:13], v[240:243], v[214:217], v[10:13]
	v_mfma_f32_16x16x32_bf16 v[6:9], v[232:235], v[222:225], v[6:9]
	v_mfma_f32_16x16x32_bf16 v[2:5], v[240:243], v[222:225], v[2:5]
	s_barrier
	s_add_i32 s8, s8, 2
	s_add_u32 s6, s6, 0x100
	s_addc_u32 s7, s7, 0
	s_cmp_lt_u32 s8, 14
	s_cbranch_scc1 .LBB0_914
	s_setprio 0
	s_waitcnt vmcnt(0)
	s_cmpk_gt_u32 s38, 0xff
	s_cbranch_scc1 .LBB0_917
	s_barrier

.Lkprio_3:
.LBB0_1128:
	s_add_u32 s38, s6, 0xf8cd0080
	s_addc_u32 s39, s7, -1
	s_cmp_lg_u32 s37, 40
	s_cselect_b32 s39, s39, 0
	s_cselect_b32 s38, s38, 0
	s_add_i32 s40, 0, 0x10000
	v_add_u32_e32 v164, s40, v169
	ds_read_b128 v[172:175], v164
	ds_read_b128 v[176:179], v164 offset:1024
	ds_read_b128 v[180:183], v164 offset:2048
	ds_read_b128 v[184:187], v164 offset:3072
	v_lshl_add_u64 v[240:241], v[150:151], 0, s[38:39]
	v_lshl_add_u64 v[164:165], v[148:149], 0, s[38:39]
	v_lshl_add_u64 v[222:223], v[152:153], 0, s[6:7]
	s_add_i32 m0, s28, 0xc000
	ds_read_b128 v[188:191], v170
	ds_read_b128 v[192:195], v170 offset:1024
	ds_read_b128 v[196:199], v170 offset:2048
	ds_read_b128 v[200:203], v170 offset:3072
	ds_read_b128 v[204:207], v170 offset:4096
	ds_read_b128 v[210:213], v170 offset:5120
	ds_read_b128 v[214:217], v170 offset:6144
	ds_read_b128 v[218:221], v170 offset:7168
	global_load_lds_dwordx4 v[222:223], off
	v_lshl_add_u64 v[222:223], v[162:163], 0, s[6:7]
	s_add_i32 m0, s28, 0xe000
	s_nop 0
	global_load_lds_dwordx4 v[222:223], off
	s_waitcnt lgkmcnt(8)
	s_barrier
	s_waitcnt lgkmcnt(7)
	v_mfma_f32_16x16x32_bf16 v[126:129], v[172:175], v[188:191], v[126:129]
	v_mfma_f32_16x16x32_bf16 v[122:125], v[180:183], v[188:191], v[122:125]
	s_waitcnt lgkmcnt(5)
	v_mfma_f32_16x16x32_bf16 v[118:121], v[172:175], v[196:199], v[118:121]
	v_mfma_f32_16x16x32_bf16 v[114:117], v[180:183], v[196:199], v[114:117]
	s_waitcnt lgkmcnt(3)
	v_mfma_f32_16x16x32_bf16 v[110:113], v[172:175], v[204:207], v[110:113]
	v_mfma_f32_16x16x32_bf16 v[106:109], v[180:183], v[204:207], v[106:109]
	s_waitcnt lgkmcnt(1)
	v_mfma_f32_16x16x32_bf16 v[102:105], v[172:175], v[214:217], v[102:105]
	v_mfma_f32_16x16x32_bf16 v[98:101], v[180:183], v[214:217], v[98:101]
	v_mfma_f32_16x16x32_bf16 v[126:129], v[176:179], v[192:195], v[126:129]
	v_mfma_f32_16x16x32_bf16 v[122:125], v[184:187], v[192:195], v[122:125]
	v_mfma_f32_16x16x32_bf16 v[118:121], v[176:179], v[200:203], v[118:121]
	v_mfma_f32_16x16x32_bf16 v[114:117], v[184:187], v[200:203], v[114:117]
	v_mfma_f32_16x16x32_bf16 v[110:113], v[176:179], v[210:213], v[110:113]
	v_mfma_f32_16x16x32_bf16 v[106:109], v[184:187], v[210:213], v[106:109]
	s_waitcnt lgkmcnt(0)
	v_mfma_f32_16x16x32_bf16 v[102:105], v[176:179], v[218:221], v[102:105]
	v_mfma_f32_16x16x32_bf16 v[98:101], v[184:187], v[218:221], v[98:101]
	s_barrier
	s_add_i32 s38, 0, 0x14000
	s_add_i32 s39, s40, s27
	v_add_u32_e32 v171, s38, v169
	v_lshl_add_u64 v[242:243], v[164:165], 0, v[138:139]
	s_mov_b32 m0, s39
	ds_read_b128 v[222:225], v171
	ds_read_b128 v[228:231], v171 offset:1024
	ds_read_b128 v[232:235], v171 offset:2048
	ds_read_b128 v[236:239], v171 offset:3072
	global_load_lds_dwordx4 v[242:243], off
	v_lshl_add_u64 v[244:245], v[164:165], 0, v[146:147]
	s_add_i32 m0, s39, 0x2000
	s_nop 0
	global_load_lds_dwordx4 v[244:245], off
	s_barrier
	s_waitcnt lgkmcnt(3)
	v_mfma_f32_16x16x32_bf16 v[94:97], v[222:225], v[188:191], v[94:97]
	s_waitcnt lgkmcnt(1)
	v_mfma_f32_16x16x32_bf16 v[90:93], v[232:235], v[188:191], v[90:93]
	v_mfma_f32_16x16x32_bf16 v[86:89], v[222:225], v[196:199], v[86:89]
	v_mfma_f32_16x16x32_bf16 v[82:85], v[232:235], v[196:199], v[82:85]
	v_mfma_f32_16x16x32_bf16 v[78:81], v[222:225], v[204:207], v[78:81]
	v_mfma_f32_16x16x32_bf16 v[74:77], v[232:235], v[204:207], v[74:77]
	v_mfma_f32_16x16x32_bf16 v[70:73], v[222:225], v[214:217], v[70:73]
	v_mfma_f32_16x16x32_bf16 v[66:69], v[232:235], v[214:217], v[66:69]
	v_mfma_f32_16x16x32_bf16 v[94:97], v[228:231], v[192:195], v[94:97]
	s_waitcnt lgkmcnt(0)
	v_mfma_f32_16x16x32_bf16 v[90:93], v[236:239], v[192:195], v[90:93]
	v_mfma_f32_16x16x32_bf16 v[86:89], v[228:231], v[200:203], v[86:89]
	v_mfma_f32_16x16x32_bf16 v[82:85], v[236:239], v[200:203], v[82:85]
	v_mfma_f32_16x16x32_bf16 v[78:81], v[228:231], v[210:213], v[78:81]
	v_mfma_f32_16x16x32_bf16 v[74:77], v[236:239], v[210:213], v[74:77]
	v_mfma_f32_16x16x32_bf16 v[70:73], v[228:231], v[218:221], v[70:73]
	v_mfma_f32_16x16x32_bf16 v[66:69], v[236:239], v[218:221], v[66:69]
	s_barrier
	s_mov_b32 m0, s28
	v_lshl_add_u64 v[246:247], v[240:241], 0, v[138:139]
	ds_read_b128 v[188:191], v170 offset:16384
	ds_read_b128 v[192:195], v170 offset:17408
	ds_read_b128 v[196:199], v170 offset:18432
	ds_read_b128 v[200:203], v170 offset:19456
	ds_read_b128 v[204:207], v170 offset:20480
	ds_read_b128 v[210:213], v170 offset:21504
	ds_read_b128 v[214:217], v170 offset:22528
	ds_read_b128 v[218:221], v170 offset:23552
	global_load_lds_dwordx4 v[246:247], off
	v_lshl_add_u64 v[248:249], v[240:241], 0, v[146:147]
	s_mov_b32 m0, s29
	s_nop 0
	global_load_lds_dwordx4 v[248:249], off
	s_barrier
	s_waitcnt lgkmcnt(7)
	v_mfma_f32_16x16x32_bf16 v[62:65], v[172:175], v[188:191], v[62:65]
	v_mfma_f32_16x16x32_bf16 v[58:61], v[180:183], v[188:191], v[58:61]
	s_waitcnt lgkmcnt(5)
	v_mfma_f32_16x16x32_bf16 v[54:57], v[172:175], v[196:199], v[54:57]
	v_mfma_f32_16x16x32_bf16 v[50:53], v[180:183], v[196:199], v[50:53]
	s_waitcnt lgkmcnt(3)
	v_mfma_f32_16x16x32_bf16 v[46:49], v[172:175], v[204:207], v[46:49]
	v_mfma_f32_16x16x32_bf16 v[42:45], v[180:183], v[204:207], v[42:45]
	s_waitcnt lgkmcnt(1)
	v_mfma_f32_16x16x32_bf16 v[38:41], v[172:175], v[214:217], v[38:41]
	v_mfma_f32_16x16x32_bf16 v[34:37], v[180:183], v[214:217], v[34:37]
	v_mfma_f32_16x16x32_bf16 v[62:65], v[176:179], v[192:195], v[62:65]
	v_mfma_f32_16x16x32_bf16 v[58:61], v[184:187], v[192:195], v[58:61]
	v_mfma_f32_16x16x32_bf16 v[54:57], v[176:179], v[200:203], v[54:57]
	v_mfma_f32_16x16x32_bf16 v[50:53], v[184:187], v[200:203], v[50:53]
	v_mfma_f32_16x16x32_bf16 v[46:49], v[176:179], v[210:213], v[46:49]
	v_mfma_f32_16x16x32_bf16 v[42:45], v[184:187], v[210:213], v[42:45]
	s_waitcnt lgkmcnt(0)
	v_mfma_f32_16x16x32_bf16 v[38:41], v[176:179], v[218:221], v[38:41]
	v_mfma_f32_16x16x32_bf16 v[34:37], v[184:187], v[218:221], v[34:37]
	s_barrier
	v_lshl_add_u64 v[172:173], v[164:165], 0, s[16:17]
	s_add_i32 s38, s38, s27
	v_lshl_add_u64 v[174:175], v[172:173], 0, v[138:139]
	s_mov_b32 m0, s38
	v_lshl_add_u64 v[172:173], v[172:173], 0, v[146:147]
	global_load_lds_dwordx4 v[174:175], off
	s_add_i32 m0, s38, 0x2000
	s_nop 0
	global_load_lds_dwordx4 v[172:173], off
	s_waitcnt vmcnt(6)
	s_barrier
	v_mfma_f32_16x16x32_bf16 v[30:33], v[222:225], v[188:191], v[30:33]
	v_mfma_f32_16x16x32_bf16 v[26:29], v[232:235], v[188:191], v[26:29]
	v_mfma_f32_16x16x32_bf16 v[22:25], v[222:225], v[196:199], v[22:25]
	v_mfma_f32_16x16x32_bf16 v[18:21], v[232:235], v[196:199], v[18:21]
	v_mfma_f32_16x16x32_bf16 v[14:17], v[222:225], v[204:207], v[14:17]
	v_mfma_f32_16x16x32_bf16 v[10:13], v[232:235], v[204:207], v[10:13]
	v_mfma_f32_16x16x32_bf16 v[6:9], v[222:225], v[214:217], v[6:9]
	v_mfma_f32_16x16x32_bf16 v[2:5], v[232:235], v[214:217], v[2:5]
	v_mfma_f32_16x16x32_bf16 v[30:33], v[228:231], v[192:195], v[30:33]
	v_mfma_f32_16x16x32_bf16 v[26:29], v[236:239], v[192:195], v[26:29]
	v_mfma_f32_16x16x32_bf16 v[22:25], v[228:231], v[200:203], v[22:25]
	v_mfma_f32_16x16x32_bf16 v[18:21], v[236:239], v[200:203], v[18:21]
	v_mfma_f32_16x16x32_bf16 v[14:17], v[228:231], v[210:213], v[14:17]
	v_mfma_f32_16x16x32_bf16 v[10:13], v[236:239], v[210:213], v[10:13]
	v_mfma_f32_16x16x32_bf16 v[6:9], v[228:231], v[218:221], v[6:9]
	v_mfma_f32_16x16x32_bf16 v[2:5], v[236:239], v[218:221], v[2:5]
	s_barrier
	s_add_i32 s38, 0, 0x18000
	v_add_u32_e32 v171, s38, v169
	ds_read_b128 v[172:175], v171
	ds_read_b128 v[176:179], v171 offset:1024
	ds_read_b128 v[180:183], v171 offset:2048
	ds_read_b128 v[184:187], v171 offset:3072
	v_lshl_add_u64 v[222:223], v[240:241], 0, s[16:17]
	s_mov_b32 m0, s31
	v_lshl_add_u64 v[224:225], v[222:223], 0, v[138:139]
	ds_read_b128 v[188:191], v170 offset:32768
	ds_read_b128 v[192:195], v170 offset:33792
	ds_read_b128 v[196:199], v170 offset:34816
	ds_read_b128 v[200:203], v170 offset:35840
	ds_read_b128 v[204:207], v170 offset:36864
	ds_read_b128 v[210:213], v170 offset:37888
	ds_read_b128 v[214:217], v170 offset:38912
	ds_read_b128 v[218:221], v170 offset:39936
	global_load_lds_dwordx4 v[224:225], off
	v_lshl_add_u64 v[222:223], v[222:223], 0, v[146:147]
	s_mov_b32 m0, s34
	s_nop 0
	global_load_lds_dwordx4 v[222:223], off
	s_waitcnt lgkmcnt(8)
	s_barrier
	s_waitcnt lgkmcnt(7)
	v_mfma_f32_16x16x32_bf16 v[126:129], v[172:175], v[188:191], v[126:129]
	v_mfma_f32_16x16x32_bf16 v[122:125], v[180:183], v[188:191], v[122:125]
	s_waitcnt lgkmcnt(5)
	v_mfma_f32_16x16x32_bf16 v[118:121], v[172:175], v[196:199], v[118:121]
	v_mfma_f32_16x16x32_bf16 v[114:117], v[180:183], v[196:199], v[114:117]
	s_waitcnt lgkmcnt(3)
	v_mfma_f32_16x16x32_bf16 v[110:113], v[172:175], v[204:207], v[110:113]
	v_mfma_f32_16x16x32_bf16 v[106:109], v[180:183], v[204:207], v[106:109]
	s_waitcnt lgkmcnt(1)
	v_mfma_f32_16x16x32_bf16 v[102:105], v[172:175], v[214:217], v[102:105]
	v_mfma_f32_16x16x32_bf16 v[98:101], v[180:183], v[214:217], v[98:101]
	v_mfma_f32_16x16x32_bf16 v[126:129], v[176:179], v[192:195], v[126:129]
	v_mfma_f32_16x16x32_bf16 v[122:125], v[184:187], v[192:195], v[122:125]
	v_mfma_f32_16x16x32_bf16 v[118:121], v[176:179], v[200:203], v[118:121]
	v_mfma_f32_16x16x32_bf16 v[114:117], v[184:187], v[200:203], v[114:117]
	v_mfma_f32_16x16x32_bf16 v[110:113], v[176:179], v[210:213], v[110:113]
	v_mfma_f32_16x16x32_bf16 v[106:109], v[184:187], v[210:213], v[106:109]
	s_waitcnt lgkmcnt(0)
	v_mfma_f32_16x16x32_bf16 v[102:105], v[176:179], v[218:221], v[102:105]
	v_mfma_f32_16x16x32_bf16 v[98:101], v[184:187], v[218:221], v[98:101]
	s_barrier
	s_add_i32 s39, 0, 0x1c000
	s_add_i32 s38, s38, s27
	v_add_u32_e32 v171, s39, v169
	v_lshl_add_u64 v[240:241], v[242:243], 0, s[18:19]
	s_mov_b32 m0, s38
	ds_read_b128 v[222:225], v171
	ds_read_b128 v[228:231], v171 offset:1024
	ds_read_b128 v[232:235], v171 offset:2048
	ds_read_b128 v[236:239], v171 offset:3072
	global_load_lds_dwordx4 v[240:241], off
	v_lshl_add_u64 v[240:241], v[244:245], 0, s[18:19]
	s_add_i32 m0, s38, 0x2000
	s_nop 0
	global_load_lds_dwordx4 v[240:241], off
	s_barrier
	s_waitcnt lgkmcnt(3)
	v_mfma_f32_16x16x32_bf16 v[94:97], v[222:225], v[188:191], v[94:97]
	s_waitcnt lgkmcnt(1)
	v_mfma_f32_16x16x32_bf16 v[90:93], v[232:235], v[188:191], v[90:93]
	v_mfma_f32_16x16x32_bf16 v[86:89], v[222:225], v[196:199], v[86:89]
	v_mfma_f32_16x16x32_bf16 v[82:85], v[232:235], v[196:199], v[82:85]
	v_mfma_f32_16x16x32_bf16 v[78:81], v[222:225], v[204:207], v[78:81]
	v_mfma_f32_16x16x32_bf16 v[74:77], v[232:235], v[204:207], v[74:77]
	v_mfma_f32_16x16x32_bf16 v[70:73], v[222:225], v[214:217], v[70:73]
	v_mfma_f32_16x16x32_bf16 v[66:69], v[232:235], v[214:217], v[66:69]
	v_mfma_f32_16x16x32_bf16 v[94:97], v[228:231], v[192:195], v[94:97]
	s_waitcnt lgkmcnt(0)
	v_mfma_f32_16x16x32_bf16 v[90:93], v[236:239], v[192:195], v[90:93]
	v_mfma_f32_16x16x32_bf16 v[86:89], v[228:231], v[200:203], v[86:89]
	v_mfma_f32_16x16x32_bf16 v[82:85], v[236:239], v[200:203], v[82:85]
	v_mfma_f32_16x16x32_bf16 v[78:81], v[228:231], v[210:213], v[78:81]
	v_mfma_f32_16x16x32_bf16 v[74:77], v[236:239], v[210:213], v[74:77]
	v_mfma_f32_16x16x32_bf16 v[70:73], v[228:231], v[218:221], v[70:73]
	v_mfma_f32_16x16x32_bf16 v[66:69], v[236:239], v[218:221], v[66:69]
	s_barrier
	s_mov_b32 m0, s35
	v_lshl_add_u64 v[240:241], v[246:247], 0, s[18:19]
	ds_read_b128 v[188:191], v170 offset:49152
	ds_read_b128 v[192:195], v170 offset:50176
	ds_read_b128 v[196:199], v170 offset:51200
	ds_read_b128 v[200:203], v170 offset:52224
	ds_read_b128 v[204:207], v170 offset:53248
	ds_read_b128 v[210:213], v170 offset:54272
	ds_read_b128 v[214:217], v170 offset:55296
	ds_read_b128 v[218:221], v170 offset:56320
	global_load_lds_dwordx4 v[240:241], off
	v_lshl_add_u64 v[240:241], v[248:249], 0, s[18:19]
	s_mov_b32 m0, s36
	s_nop 0
	global_load_lds_dwordx4 v[240:241], off
	s_barrier
	s_waitcnt lgkmcnt(7)
	v_mfma_f32_16x16x32_bf16 v[62:65], v[172:175], v[188:191], v[62:65]
	v_mfma_f32_16x16x32_bf16 v[58:61], v[180:183], v[188:191], v[58:61]
	s_waitcnt lgkmcnt(5)
	v_mfma_f32_16x16x32_bf16 v[54:57], v[172:175], v[196:199], v[54:57]
	v_mfma_f32_16x16x32_bf16 v[50:53], v[180:183], v[196:199], v[50:53]
	s_waitcnt lgkmcnt(3)
	v_mfma_f32_16x16x32_bf16 v[46:49], v[172:175], v[204:207], v[46:49]
	v_mfma_f32_16x16x32_bf16 v[42:45], v[180:183], v[204:207], v[42:45]
	s_waitcnt lgkmcnt(1)
	v_mfma_f32_16x16x32_bf16 v[38:41], v[172:175], v[214:217], v[38:41]
	v_mfma_f32_16x16x32_bf16 v[34:37], v[180:183], v[214:217], v[34:37]
	v_mfma_f32_16x16x32_bf16 v[62:65], v[176:179], v[192:195], v[62:65]
	v_mfma_f32_16x16x32_bf16 v[58:61], v[184:187], v[192:195], v[58:61]
	v_mfma_f32_16x16x32_bf16 v[54:57], v[176:179], v[200:203], v[54:57]
	v_mfma_f32_16x16x32_bf16 v[50:53], v[184:187], v[200:203], v[50:53]
	v_mfma_f32_16x16x32_bf16 v[46:49], v[176:179], v[210:213], v[46:49]
	v_mfma_f32_16x16x32_bf16 v[42:45], v[184:187], v[210:213], v[42:45]
	s_waitcnt lgkmcnt(0)
	v_mfma_f32_16x16x32_bf16 v[38:41], v[176:179], v[218:221], v[38:41]
	v_mfma_f32_16x16x32_bf16 v[34:37], v[184:187], v[218:221], v[34:37]
	s_barrier
	v_lshl_add_u64 v[164:165], v[164:165], 0, s[20:21]
	s_add_i32 s38, s39, s27
	v_lshl_add_u64 v[172:173], v[164:165], 0, v[138:139]
	s_mov_b32 m0, s38
	v_lshl_add_u64 v[164:165], v[164:165], 0, v[146:147]
	global_load_lds_dwordx4 v[172:173], off
	s_add_i32 m0, s38, 0x2000
	s_nop 0
	global_load_lds_dwordx4 v[164:165], off
	s_waitcnt vmcnt(6)
	s_barrier
	v_mfma_f32_16x16x32_bf16 v[30:33], v[222:225], v[188:191], v[30:33]
	v_mfma_f32_16x16x32_bf16 v[26:29], v[232:235], v[188:191], v[26:29]
	v_mfma_f32_16x16x32_bf16 v[22:25], v[222:225], v[196:199], v[22:25]
	v_mfma_f32_16x16x32_bf16 v[18:21], v[232:235], v[196:199], v[18:21]
	v_mfma_f32_16x16x32_bf16 v[14:17], v[222:225], v[204:207], v[14:17]
	v_mfma_f32_16x16x32_bf16 v[10:13], v[232:235], v[204:207], v[10:13]
	v_mfma_f32_16x16x32_bf16 v[6:9], v[222:225], v[214:217], v[6:9]
	v_mfma_f32_16x16x32_bf16 v[2:5], v[232:235], v[214:217], v[2:5]
	v_mfma_f32_16x16x32_bf16 v[30:33], v[228:231], v[192:195], v[30:33]
	v_mfma_f32_16x16x32_bf16 v[26:29], v[236:239], v[192:195], v[26:29]
	v_mfma_f32_16x16x32_bf16 v[22:25], v[228:231], v[200:203], v[22:25]
	v_mfma_f32_16x16x32_bf16 v[18:21], v[236:239], v[200:203], v[18:21]
	v_mfma_f32_16x16x32_bf16 v[14:17], v[228:231], v[210:213], v[14:17]
	v_mfma_f32_16x16x32_bf16 v[10:13], v[236:239], v[210:213], v[10:13]
	v_mfma_f32_16x16x32_bf16 v[6:9], v[228:231], v[218:221], v[6:9]
	v_mfma_f32_16x16x32_bf16 v[2:5], v[236:239], v[218:221], v[2:5]
	s_barrier
	s_add_i32 s37, s37, 2
	s_add_u32 s6, s6, 0x100
	s_addc_u32 s7, s7, 0
	s_cmp_lt_u32 s37, 42
	s_cbranch_scc1 .LBB0_1128
	s_setprio 0
	s_waitcnt vmcnt(0)
	s_cmpk_gt_u32 s26, 0xff
	s_cbranch_scc1 .LBB0_1131
	s_barrier

.Lkprio_4:
.LBB0_1271:
	s_cmpk_eq_i32 s6, 0x700
	v_lshl_add_u64 v[170:171], v[162:163], 0, s[6:7]
	v_lshl_add_u64 v[170:171], v[170:171], 0, s[18:19]
	s_cselect_b64 vcc, -1, 0
	s_add_i32 s25, 0, 0x10000
	v_cndmask_b32_e32 v245, v171, v153, vcc
	v_add_u32_e32 v171, s25, v173
	ds_read_b128 v[176:179], v171
	ds_read_b128 v[180:183], v171 offset:1024
	ds_read_b128 v[184:187], v171 offset:2048
	ds_read_b128 v[188:191], v171 offset:3072
	v_cndmask_b32_e32 v244, v170, v152, vcc
	v_lshl_add_u64 v[170:171], v[168:169], 0, s[6:7]
	v_cndmask_b32_e32 v171, v171, v151, vcc
	v_cndmask_b32_e32 v170, v170, v150, vcc
	v_lshl_add_u64 v[228:229], v[164:165], 0, s[6:7]
	s_add_i32 m0, s20, 0xc000
	ds_read_b128 v[192:195], v174
	ds_read_b128 v[196:199], v174 offset:1024
	ds_read_b128 v[200:203], v174 offset:2048
	ds_read_b128 v[204:207], v174 offset:3072
	ds_read_b128 v[210:213], v174 offset:4096
	ds_read_b128 v[214:217], v174 offset:5120
	ds_read_b128 v[218:221], v174 offset:6144
	ds_read_b128 v[222:225], v174 offset:7168
	global_load_lds_dwordx4 v[228:229], off
	v_lshl_add_u64 v[228:229], v[166:167], 0, s[6:7]
	s_add_i32 m0, s20, 0xe000
	s_nop 0
	global_load_lds_dwordx4 v[228:229], off
	s_waitcnt lgkmcnt(8)
	s_barrier
	s_waitcnt lgkmcnt(7)
	v_mfma_f32_16x16x32_bf16 v[126:129], v[176:179], v[192:195], v[126:129]
	v_mfma_f32_16x16x32_bf16 v[122:125], v[184:187], v[192:195], v[122:125]
	s_waitcnt lgkmcnt(5)
	v_mfma_f32_16x16x32_bf16 v[118:121], v[176:179], v[200:203], v[118:121]
	v_mfma_f32_16x16x32_bf16 v[114:117], v[184:187], v[200:203], v[114:117]
	s_waitcnt lgkmcnt(3)
	v_mfma_f32_16x16x32_bf16 v[110:113], v[176:179], v[210:213], v[110:113]
	v_mfma_f32_16x16x32_bf16 v[106:109], v[184:187], v[210:213], v[106:109]
	s_waitcnt lgkmcnt(1)
	v_mfma_f32_16x16x32_bf16 v[102:105], v[176:179], v[218:221], v[102:105]
	v_mfma_f32_16x16x32_bf16 v[98:101], v[184:187], v[218:221], v[98:101]
	v_mfma_f32_16x16x32_bf16 v[126:129], v[180:183], v[196:199], v[126:129]
	v_mfma_f32_16x16x32_bf16 v[122:125], v[188:191], v[196:199], v[122:125]
	v_mfma_f32_16x16x32_bf16 v[118:121], v[180:183], v[204:207], v[118:121]
	v_mfma_f32_16x16x32_bf16 v[114:117], v[188:191], v[204:207], v[114:117]
	v_mfma_f32_16x16x32_bf16 v[110:113], v[180:183], v[214:217], v[110:113]
	v_mfma_f32_16x16x32_bf16 v[106:109], v[188:191], v[214:217], v[106:109]
	s_waitcnt lgkmcnt(0)
	v_mfma_f32_16x16x32_bf16 v[102:105], v[180:183], v[222:225], v[102:105]
	v_mfma_f32_16x16x32_bf16 v[98:101], v[188:191], v[222:225], v[98:101]
	s_barrier
	s_add_i32 s41, 0, 0x14000
	s_add_i32 s25, s25, s35
	v_add_u32_e32 v175, s41, v173
	v_lshl_add_u64 v[246:247], v[170:171], 0, v[138:139]
	s_mov_b32 m0, s25
	ds_read_b128 v[228:231], v175
	ds_read_b128 v[232:235], v175 offset:1024
	ds_read_b128 v[236:239], v175 offset:2048
	ds_read_b128 v[240:243], v175 offset:3072
	global_load_lds_dwordx4 v[246:247], off
	v_lshl_add_u64 v[248:249], v[170:171], 0, v[148:149]
	s_add_i32 m0, s25, 0x2000
	s_nop 0
	global_load_lds_dwordx4 v[248:249], off
	s_barrier
	s_waitcnt lgkmcnt(3)
	v_mfma_f32_16x16x32_bf16 v[94:97], v[228:231], v[192:195], v[94:97]
	s_waitcnt lgkmcnt(1)
	v_mfma_f32_16x16x32_bf16 v[90:93], v[236:239], v[192:195], v[90:93]
	v_mfma_f32_16x16x32_bf16 v[86:89], v[228:231], v[200:203], v[86:89]
	v_mfma_f32_16x16x32_bf16 v[82:85], v[236:239], v[200:203], v[82:85]
	v_mfma_f32_16x16x32_bf16 v[78:81], v[228:231], v[210:213], v[78:81]
	v_mfma_f32_16x16x32_bf16 v[74:77], v[236:239], v[210:213], v[74:77]
	v_mfma_f32_16x16x32_bf16 v[70:73], v[228:231], v[218:221], v[70:73]
	v_mfma_f32_16x16x32_bf16 v[66:69], v[236:239], v[218:221], v[66:69]
	v_mfma_f32_16x16x32_bf16 v[94:97], v[232:235], v[196:199], v[94:97]
	s_waitcnt lgkmcnt(0)
	v_mfma_f32_16x16x32_bf16 v[90:93], v[240:243], v[196:199], v[90:93]
	v_mfma_f32_16x16x32_bf16 v[86:89], v[232:235], v[204:207], v[86:89]
	v_mfma_f32_16x16x32_bf16 v[82:85], v[240:243], v[204:207], v[82:85]
	v_mfma_f32_16x16x32_bf16 v[78:81], v[232:235], v[214:217], v[78:81]
	v_mfma_f32_16x16x32_bf16 v[74:77], v[240:243], v[214:217], v[74:77]
	v_mfma_f32_16x16x32_bf16 v[70:73], v[232:235], v[222:225], v[70:73]
	v_mfma_f32_16x16x32_bf16 v[66:69], v[240:243], v[222:225], v[66:69]
	s_barrier
	s_mov_b32 m0, s20
	v_lshl_add_u64 v[250:251], v[244:245], 0, v[138:139]
	ds_read_b128 v[192:195], v174 offset:16384
	ds_read_b128 v[196:199], v174 offset:17408
	ds_read_b128 v[200:203], v174 offset:18432
	ds_read_b128 v[204:207], v174 offset:19456
	ds_read_b128 v[210:213], v174 offset:20480
	ds_read_b128 v[214:217], v174 offset:21504
	ds_read_b128 v[218:221], v174 offset:22528
	ds_read_b128 v[222:225], v174 offset:23552
	global_load_lds_dwordx4 v[250:251], off
	v_lshl_add_u64 v[252:253], v[244:245], 0, v[148:149]
	s_mov_b32 m0, s36
	s_nop 0
	global_load_lds_dwordx4 v[252:253], off
	s_barrier
	s_waitcnt lgkmcnt(7)
	v_mfma_f32_16x16x32_bf16 v[62:65], v[176:179], v[192:195], v[62:65]
	v_mfma_f32_16x16x32_bf16 v[58:61], v[184:187], v[192:195], v[58:61]
	s_waitcnt lgkmcnt(5)
	v_mfma_f32_16x16x32_bf16 v[54:57], v[176:179], v[200:203], v[54:57]
	v_mfma_f32_16x16x32_bf16 v[50:53], v[184:187], v[200:203], v[50:53]
	s_waitcnt lgkmcnt(3)
	v_mfma_f32_16x16x32_bf16 v[46:49], v[176:179], v[210:213], v[46:49]
	v_mfma_f32_16x16x32_bf16 v[42:45], v[184:187], v[210:213], v[42:45]
	s_waitcnt lgkmcnt(1)
	v_mfma_f32_16x16x32_bf16 v[38:41], v[176:179], v[218:221], v[38:41]
	v_mfma_f32_16x16x32_bf16 v[34:37], v[184:187], v[218:221], v[34:37]
	v_mfma_f32_16x16x32_bf16 v[62:65], v[180:183], v[196:199], v[62:65]
	v_mfma_f32_16x16x32_bf16 v[58:61], v[188:191], v[196:199], v[58:61]
	v_mfma_f32_16x16x32_bf16 v[54:57], v[180:183], v[204:207], v[54:57]
	v_mfma_f32_16x16x32_bf16 v[50:53], v[188:191], v[204:207], v[50:53]
	v_mfma_f32_16x16x32_bf16 v[46:49], v[180:183], v[214:217], v[46:49]
	v_mfma_f32_16x16x32_bf16 v[42:45], v[188:191], v[214:217], v[42:45]
	s_waitcnt lgkmcnt(0)
	v_mfma_f32_16x16x32_bf16 v[38:41], v[180:183], v[222:225], v[38:41]
	v_mfma_f32_16x16x32_bf16 v[34:37], v[188:191], v[222:225], v[34:37]
	s_barrier
	v_lshl_add_u64 v[176:177], v[170:171], 0, s[12:13]
	s_add_i32 s25, s41, s35
	v_lshl_add_u64 v[178:179], v[176:177], 0, v[138:139]
	s_mov_b32 m0, s25
	v_lshl_add_u64 v[176:177], v[176:177], 0, v[148:149]
	global_load_lds_dwordx4 v[178:179], off
	s_add_i32 m0, s25, 0x2000
	s_nop 0
	global_load_lds_dwordx4 v[176:177], off
	s_waitcnt vmcnt(6)
	s_barrier
	v_mfma_f32_16x16x32_bf16 v[30:33], v[228:231], v[192:195], v[30:33]
	v_mfma_f32_16x16x32_bf16 v[26:29], v[236:239], v[192:195], v[26:29]
	v_mfma_f32_16x16x32_bf16 v[22:25], v[228:231], v[200:203], v[22:25]
	v_mfma_f32_16x16x32_bf16 v[18:21], v[236:239], v[200:203], v[18:21]
	v_mfma_f32_16x16x32_bf16 v[14:17], v[228:231], v[210:213], v[14:17]
	v_mfma_f32_16x16x32_bf16 v[10:13], v[236:239], v[210:213], v[10:13]
	v_mfma_f32_16x16x32_bf16 v[6:9], v[228:231], v[218:221], v[6:9]
	v_mfma_f32_16x16x32_bf16 v[2:5], v[236:239], v[218:221], v[2:5]
	v_mfma_f32_16x16x32_bf16 v[30:33], v[232:235], v[196:199], v[30:33]
	v_mfma_f32_16x16x32_bf16 v[26:29], v[240:243], v[196:199], v[26:29]
	v_mfma_f32_16x16x32_bf16 v[22:25], v[232:235], v[204:207], v[22:25]
	v_mfma_f32_16x16x32_bf16 v[18:21], v[240:243], v[204:207], v[18:21]
	v_mfma_f32_16x16x32_bf16 v[14:17], v[232:235], v[214:217], v[14:17]
	v_mfma_f32_16x16x32_bf16 v[10:13], v[240:243], v[214:217], v[10:13]
	v_mfma_f32_16x16x32_bf16 v[6:9], v[232:235], v[222:225], v[6:9]
	v_mfma_f32_16x16x32_bf16 v[2:5], v[240:243], v[222:225], v[2:5]
	s_barrier
	s_add_i32 s25, 0, 0x18000
	v_add_u32_e32 v175, s25, v173
	ds_read_b128 v[176:179], v175
	ds_read_b128 v[180:183], v175 offset:1024
	ds_read_b128 v[184:187], v175 offset:2048
	ds_read_b128 v[188:191], v175 offset:3072
	v_lshl_add_u64 v[228:229], v[244:245], 0, s[12:13]
	s_mov_b32 m0, s37
	v_lshl_add_u64 v[230:231], v[228:229], 0, v[138:139]
	ds_read_b128 v[192:195], v174 offset:32768
	ds_read_b128 v[196:199], v174 offset:33792
	ds_read_b128 v[200:203], v174 offset:34816
	ds_read_b128 v[204:207], v174 offset:35840
	ds_read_b128 v[210:213], v174 offset:36864
	ds_read_b128 v[214:217], v174 offset:37888
	ds_read_b128 v[218:221], v174 offset:38912
	ds_read_b128 v[222:225], v174 offset:39936
	global_load_lds_dwordx4 v[230:231], off
	v_lshl_add_u64 v[228:229], v[228:229], 0, v[148:149]
	s_mov_b32 m0, s38
	s_nop 0
	global_load_lds_dwordx4 v[228:229], off
	s_waitcnt lgkmcnt(8)
	s_barrier
	s_waitcnt lgkmcnt(7)
	v_mfma_f32_16x16x32_bf16 v[126:129], v[176:179], v[192:195], v[126:129]
	v_mfma_f32_16x16x32_bf16 v[122:125], v[184:187], v[192:195], v[122:125]
	s_waitcnt lgkmcnt(5)
	v_mfma_f32_16x16x32_bf16 v[118:121], v[176:179], v[200:203], v[118:121]
	v_mfma_f32_16x16x32_bf16 v[114:117], v[184:187], v[200:203], v[114:117]
	s_waitcnt lgkmcnt(3)
	v_mfma_f32_16x16x32_bf16 v[110:113], v[176:179], v[210:213], v[110:113]
	v_mfma_f32_16x16x32_bf16 v[106:109], v[184:187], v[210:213], v[106:109]
	s_waitcnt lgkmcnt(1)
	v_mfma_f32_16x16x32_bf16 v[102:105], v[176:179], v[218:221], v[102:105]
	v_mfma_f32_16x16x32_bf16 v[98:101], v[184:187], v[218:221], v[98:101]
	v_mfma_f32_16x16x32_bf16 v[126:129], v[180:183], v[196:199], v[126:129]
	v_mfma_f32_16x16x32_bf16 v[122:125], v[188:191], v[196:199], v[122:125]
	v_mfma_f32_16x16x32_bf16 v[118:121], v[180:183], v[204:207], v[118:121]
	v_mfma_f32_16x16x32_bf16 v[114:117], v[188:191], v[204:207], v[114:117]
	v_mfma_f32_16x16x32_bf16 v[110:113], v[180:183], v[214:217], v[110:113]
	v_mfma_f32_16x16x32_bf16 v[106:109], v[188:191], v[214:217], v[106:109]
	s_waitcnt lgkmcnt(0)
	v_mfma_f32_16x16x32_bf16 v[102:105], v[180:183], v[222:225], v[102:105]
	v_mfma_f32_16x16x32_bf16 v[98:101], v[188:191], v[222:225], v[98:101]
	s_barrier
	s_add_i32 s41, 0, 0x1c000
	s_add_i32 s25, s25, s35
	v_add_u32_e32 v175, s41, v173
	v_lshl_add_u64 v[244:245], v[246:247], 0, s[14:15]
	s_mov_b32 m0, s25
	ds_read_b128 v[228:231], v175
	ds_read_b128 v[232:235], v175 offset:1024
	ds_read_b128 v[236:239], v175 offset:2048
	ds_read_b128 v[240:243], v175 offset:3072
	global_load_lds_dwordx4 v[244:245], off
	v_lshl_add_u64 v[244:245], v[248:249], 0, s[14:15]
	s_add_i32 m0, s25, 0x2000
	s_nop 0
	global_load_lds_dwordx4 v[244:245], off
	s_barrier
	s_waitcnt lgkmcnt(3)
	v_mfma_f32_16x16x32_bf16 v[94:97], v[228:231], v[192:195], v[94:97]
	s_waitcnt lgkmcnt(1)
	v_mfma_f32_16x16x32_bf16 v[90:93], v[236:239], v[192:195], v[90:93]
	v_mfma_f32_16x16x32_bf16 v[86:89], v[228:231], v[200:203], v[86:89]
	v_mfma_f32_16x16x32_bf16 v[82:85], v[236:239], v[200:203], v[82:85]
	v_mfma_f32_16x16x32_bf16 v[78:81], v[228:231], v[210:213], v[78:81]
	v_mfma_f32_16x16x32_bf16 v[74:77], v[236:239], v[210:213], v[74:77]
	v_mfma_f32_16x16x32_bf16 v[70:73], v[228:231], v[218:221], v[70:73]
	v_mfma_f32_16x16x32_bf16 v[66:69], v[236:239], v[218:221], v[66:69]
	v_mfma_f32_16x16x32_bf16 v[94:97], v[232:235], v[196:199], v[94:97]
	s_waitcnt lgkmcnt(0)
	v_mfma_f32_16x16x32_bf16 v[90:93], v[240:243], v[196:199], v[90:93]
	v_mfma_f32_16x16x32_bf16 v[86:89], v[232:235], v[204:207], v[86:89]
	v_mfma_f32_16x16x32_bf16 v[82:85], v[240:243], v[204:207], v[82:85]
	v_mfma_f32_16x16x32_bf16 v[78:81], v[232:235], v[214:217], v[78:81]
	v_mfma_f32_16x16x32_bf16 v[74:77], v[240:243], v[214:217], v[74:77]
	v_mfma_f32_16x16x32_bf16 v[70:73], v[232:235], v[222:225], v[70:73]
	v_mfma_f32_16x16x32_bf16 v[66:69], v[240:243], v[222:225], v[66:69]
	s_barrier
	s_mov_b32 m0, s39
	v_lshl_add_u64 v[244:245], v[250:251], 0, s[14:15]
	ds_read_b128 v[192:195], v174 offset:49152
	ds_read_b128 v[196:199], v174 offset:50176
	ds_read_b128 v[200:203], v174 offset:51200
	ds_read_b128 v[204:207], v174 offset:52224
	ds_read_b128 v[210:213], v174 offset:53248
	ds_read_b128 v[214:217], v174 offset:54272
	ds_read_b128 v[218:221], v174 offset:55296
	ds_read_b128 v[222:225], v174 offset:56320
	global_load_lds_dwordx4 v[244:245], off
	v_lshl_add_u64 v[244:245], v[252:253], 0, s[14:15]
	s_mov_b32 m0, s40
	s_nop 0
	global_load_lds_dwordx4 v[244:245], off
	s_barrier
	s_waitcnt lgkmcnt(7)
	v_mfma_f32_16x16x32_bf16 v[62:65], v[176:179], v[192:195], v[62:65]
	v_mfma_f32_16x16x32_bf16 v[58:61], v[184:187], v[192:195], v[58:61]
	s_waitcnt lgkmcnt(5)
	v_mfma_f32_16x16x32_bf16 v[54:57], v[176:179], v[200:203], v[54:57]
	v_mfma_f32_16x16x32_bf16 v[50:53], v[184:187], v[200:203], v[50:53]
	s_waitcnt lgkmcnt(3)
	v_mfma_f32_16x16x32_bf16 v[46:49], v[176:179], v[210:213], v[46:49]
	v_mfma_f32_16x16x32_bf16 v[42:45], v[184:187], v[210:213], v[42:45]
	s_waitcnt lgkmcnt(1)
	v_mfma_f32_16x16x32_bf16 v[38:41], v[176:179], v[218:221], v[38:41]
	v_mfma_f32_16x16x32_bf16 v[34:37], v[184:187], v[218:221], v[34:37]
	v_mfma_f32_16x16x32_bf16 v[62:65], v[180:183], v[196:199], v[62:65]
	v_mfma_f32_16x16x32_bf16 v[58:61], v[188:191], v[196:199], v[58:61]
	v_mfma_f32_16x16x32_bf16 v[54:57], v[180:183], v[204:207], v[54:57]
	v_mfma_f32_16x16x32_bf16 v[50:53], v[188:191], v[204:207], v[50:53]
	v_mfma_f32_16x16x32_bf16 v[46:49], v[180:183], v[214:217], v[46:49]
	v_mfma_f32_16x16x32_bf16 v[42:45], v[188:191], v[214:217], v[42:45]
	s_waitcnt lgkmcnt(0)
	v_mfma_f32_16x16x32_bf16 v[38:41], v[180:183], v[222:225], v[38:41]
	v_mfma_f32_16x16x32_bf16 v[34:37], v[188:191], v[222:225], v[34:37]
	s_barrier
	v_lshl_add_u64 v[170:171], v[170:171], 0, s[16:17]
	s_add_i32 s25, s41, s35
	v_lshl_add_u64 v[176:177], v[170:171], 0, v[138:139]
	s_mov_b32 m0, s25
	v_lshl_add_u64 v[170:171], v[170:171], 0, v[148:149]
	global_load_lds_dwordx4 v[176:177], off
	s_add_i32 m0, s25, 0x2000
	s_nop 0
	global_load_lds_dwordx4 v[170:171], off
	s_waitcnt vmcnt(6)
	s_barrier
	v_mfma_f32_16x16x32_bf16 v[30:33], v[228:231], v[192:195], v[30:33]
	v_mfma_f32_16x16x32_bf16 v[26:29], v[236:239], v[192:195], v[26:29]
	v_mfma_f32_16x16x32_bf16 v[22:25], v[228:231], v[200:203], v[22:25]
	v_mfma_f32_16x16x32_bf16 v[18:21], v[236:239], v[200:203], v[18:21]
	v_mfma_f32_16x16x32_bf16 v[14:17], v[228:231], v[210:213], v[14:17]
	v_mfma_f32_16x16x32_bf16 v[10:13], v[236:239], v[210:213], v[10:13]
	v_mfma_f32_16x16x32_bf16 v[6:9], v[228:231], v[218:221], v[6:9]
	v_mfma_f32_16x16x32_bf16 v[2:5], v[236:239], v[218:221], v[2:5]
	v_mfma_f32_16x16x32_bf16 v[30:33], v[232:235], v[196:199], v[30:33]
	v_mfma_f32_16x16x32_bf16 v[26:29], v[240:243], v[196:199], v[26:29]
	v_mfma_f32_16x16x32_bf16 v[22:25], v[232:235], v[204:207], v[22:25]
	v_mfma_f32_16x16x32_bf16 v[18:21], v[240:243], v[204:207], v[18:21]
	v_mfma_f32_16x16x32_bf16 v[14:17], v[232:235], v[214:217], v[14:17]
	v_mfma_f32_16x16x32_bf16 v[10:13], v[240:243], v[214:217], v[10:13]
	v_mfma_f32_16x16x32_bf16 v[6:9], v[232:235], v[222:225], v[6:9]
	v_mfma_f32_16x16x32_bf16 v[2:5], v[240:243], v[222:225], v[2:5]
	s_barrier
	s_add_i32 s24, s24, 2
	s_add_u32 s6, s6, 0x100
	s_addc_u32 s7, s7, 0
	s_cmp_lt_u32 s24, 14
	s_cbranch_scc1 .LBB0_1271
	s_setprio 0
	s_waitcnt vmcnt(0)
	s_cmpk_gt_u32 s27, 0xff
	s_cbranch_scc1 .LBB0_1274
	s_barrier

.Lkprio_5:
.LBB0_1645:
	s_add_u32 s33, s6, 0xfbd40080
	s_addc_u32 s34, s7, -1
	s_cmp_lg_u32 s31, 12
	s_cselect_b32 s35, s34, 0
	s_cselect_b32 s34, s33, 0
	s_add_i32 s33, 0, 0x10000
	v_add_u32_e32 v164, s33, v167
	ds_read_b128 v[170:173], v164
	ds_read_b128 v[174:177], v164 offset:1024
	ds_read_b128 v[178:181], v164 offset:2048
	ds_read_b128 v[182:185], v164 offset:3072
	v_lshl_add_u64 v[206:207], v[150:151], 0, s[34:35]
	v_lshl_add_u64 v[164:165], v[148:149], 0, s[34:35]
	v_lshl_add_u64 v[222:223], v[152:153], 0, s[6:7]
	s_add_i32 m0, s17, 0xc000
	ds_read_b128 v[186:189], v168
	ds_read_b128 v[190:193], v168 offset:1024
	ds_read_b128 v[194:197], v168 offset:2048
	ds_read_b128 v[198:201], v168 offset:3072
	ds_read_b128 v[202:205], v168 offset:4096
	ds_read_b128 v[210:213], v168 offset:5120
	ds_read_b128 v[214:217], v168 offset:6144
	ds_read_b128 v[218:221], v168 offset:7168
	global_load_lds_dwordx4 v[222:223], off
	v_lshl_add_u64 v[222:223], v[162:163], 0, s[6:7]
	s_add_i32 m0, s17, 0xe000
	s_nop 0
	global_load_lds_dwordx4 v[222:223], off
	s_waitcnt lgkmcnt(8)
	s_barrier
	s_waitcnt lgkmcnt(7)
	v_mfma_f32_16x16x32_bf16 v[126:129], v[170:173], v[186:189], v[126:129]
	v_mfma_f32_16x16x32_bf16 v[122:125], v[178:181], v[186:189], v[122:125]
	s_waitcnt lgkmcnt(5)
	v_mfma_f32_16x16x32_bf16 v[118:121], v[170:173], v[194:197], v[118:121]
	v_mfma_f32_16x16x32_bf16 v[114:117], v[178:181], v[194:197], v[114:117]
	s_waitcnt lgkmcnt(3)
	v_mfma_f32_16x16x32_bf16 v[110:113], v[170:173], v[202:205], v[110:113]
	v_mfma_f32_16x16x32_bf16 v[106:109], v[178:181], v[202:205], v[106:109]
	s_waitcnt lgkmcnt(1)
	v_mfma_f32_16x16x32_bf16 v[102:105], v[170:173], v[214:217], v[102:105]
	v_mfma_f32_16x16x32_bf16 v[98:101], v[178:181], v[214:217], v[98:101]
	v_mfma_f32_16x16x32_bf16 v[126:129], v[174:177], v[190:193], v[126:129]
	v_mfma_f32_16x16x32_bf16 v[122:125], v[182:185], v[190:193], v[122:125]
	v_mfma_f32_16x16x32_bf16 v[118:121], v[174:177], v[198:201], v[118:121]
	v_mfma_f32_16x16x32_bf16 v[114:117], v[182:185], v[198:201], v[114:117]
	v_mfma_f32_16x16x32_bf16 v[110:113], v[174:177], v[210:213], v[110:113]
	v_mfma_f32_16x16x32_bf16 v[106:109], v[182:185], v[210:213], v[106:109]
	s_waitcnt lgkmcnt(0)
	v_mfma_f32_16x16x32_bf16 v[102:105], v[174:177], v[218:221], v[102:105]
	v_mfma_f32_16x16x32_bf16 v[98:101], v[182:185], v[218:221], v[98:101]
	s_barrier
	s_add_i32 s34, 0, 0x14000
	s_add_i32 s33, s33, s25
	v_add_u32_e32 v169, s34, v167
	v_lshl_add_u64 v[240:241], v[164:165], 0, v[138:139]
	s_mov_b32 m0, s33
	ds_read_b128 v[222:225], v169
	ds_read_b128 v[228:231], v169 offset:1024
	ds_read_b128 v[232:235], v169 offset:2048
	ds_read_b128 v[236:239], v169 offset:3072
	global_load_lds_dwordx4 v[240:241], off
	v_lshl_add_u64 v[242:243], v[164:165], 0, v[146:147]
	s_add_i32 m0, s33, 0x2000
	s_nop 0
	global_load_lds_dwordx4 v[242:243], off
	s_barrier
	s_waitcnt lgkmcnt(3)
	v_mfma_f32_16x16x32_bf16 v[94:97], v[222:225], v[186:189], v[94:97]
	s_waitcnt lgkmcnt(1)
	v_mfma_f32_16x16x32_bf16 v[90:93], v[232:235], v[186:189], v[90:93]
	v_mfma_f32_16x16x32_bf16 v[86:89], v[222:225], v[194:197], v[86:89]
	v_mfma_f32_16x16x32_bf16 v[82:85], v[232:235], v[194:197], v[82:85]
	v_mfma_f32_16x16x32_bf16 v[78:81], v[222:225], v[202:205], v[78:81]
	v_mfma_f32_16x16x32_bf16 v[74:77], v[232:235], v[202:205], v[74:77]
	v_mfma_f32_16x16x32_bf16 v[70:73], v[222:225], v[214:217], v[70:73]
	v_mfma_f32_16x16x32_bf16 v[66:69], v[232:235], v[214:217], v[66:69]
	v_mfma_f32_16x16x32_bf16 v[94:97], v[228:231], v[190:193], v[94:97]
	s_waitcnt lgkmcnt(0)
	v_mfma_f32_16x16x32_bf16 v[90:93], v[236:239], v[190:193], v[90:93]
	v_mfma_f32_16x16x32_bf16 v[86:89], v[228:231], v[198:201], v[86:89]
	v_mfma_f32_16x16x32_bf16 v[82:85], v[236:239], v[198:201], v[82:85]
	v_mfma_f32_16x16x32_bf16 v[78:81], v[228:231], v[210:213], v[78:81]
	v_mfma_f32_16x16x32_bf16 v[74:77], v[236:239], v[210:213], v[74:77]
	v_mfma_f32_16x16x32_bf16 v[70:73], v[228:231], v[218:221], v[70:73]
	v_mfma_f32_16x16x32_bf16 v[66:69], v[236:239], v[218:221], v[66:69]
	s_barrier
	s_mov_b32 m0, s17
	v_lshl_add_u64 v[244:245], v[206:207], 0, v[138:139]
	ds_read_b128 v[186:189], v168 offset:16384
	ds_read_b128 v[190:193], v168 offset:17408
	ds_read_b128 v[194:197], v168 offset:18432
	ds_read_b128 v[198:201], v168 offset:19456
	ds_read_b128 v[202:205], v168 offset:20480
	ds_read_b128 v[210:213], v168 offset:21504
	ds_read_b128 v[214:217], v168 offset:22528
	ds_read_b128 v[218:221], v168 offset:23552
	global_load_lds_dwordx4 v[244:245], off
	v_lshl_add_u64 v[246:247], v[206:207], 0, v[146:147]
	s_mov_b32 m0, s26
	s_nop 0
	global_load_lds_dwordx4 v[246:247], off
	s_barrier
	s_waitcnt lgkmcnt(7)
	v_mfma_f32_16x16x32_bf16 v[62:65], v[170:173], v[186:189], v[62:65]
	v_mfma_f32_16x16x32_bf16 v[58:61], v[178:181], v[186:189], v[58:61]
	s_waitcnt lgkmcnt(5)
	v_mfma_f32_16x16x32_bf16 v[54:57], v[170:173], v[194:197], v[54:57]
	v_mfma_f32_16x16x32_bf16 v[50:53], v[178:181], v[194:197], v[50:53]
	s_waitcnt lgkmcnt(3)
	v_mfma_f32_16x16x32_bf16 v[46:49], v[170:173], v[202:205], v[46:49]
	v_mfma_f32_16x16x32_bf16 v[42:45], v[178:181], v[202:205], v[42:45]
	s_waitcnt lgkmcnt(1)
	v_mfma_f32_16x16x32_bf16 v[38:41], v[170:173], v[214:217], v[38:41]
	v_mfma_f32_16x16x32_bf16 v[34:37], v[178:181], v[214:217], v[34:37]
	v_mfma_f32_16x16x32_bf16 v[62:65], v[174:177], v[190:193], v[62:65]
	v_mfma_f32_16x16x32_bf16 v[58:61], v[182:185], v[190:193], v[58:61]
	v_mfma_f32_16x16x32_bf16 v[54:57], v[174:177], v[198:201], v[54:57]
	v_mfma_f32_16x16x32_bf16 v[50:53], v[182:185], v[198:201], v[50:53]
	v_mfma_f32_16x16x32_bf16 v[46:49], v[174:177], v[210:213], v[46:49]
	v_mfma_f32_16x16x32_bf16 v[42:45], v[182:185], v[210:213], v[42:45]
	s_waitcnt lgkmcnt(0)
	v_mfma_f32_16x16x32_bf16 v[38:41], v[174:177], v[218:221], v[38:41]
	v_mfma_f32_16x16x32_bf16 v[34:37], v[182:185], v[218:221], v[34:37]
	s_barrier
	v_lshl_add_u64 v[170:171], v[164:165], 0, s[8:9]
	s_add_i32 s33, s34, s25
	v_lshl_add_u64 v[172:173], v[170:171], 0, v[138:139]
	s_mov_b32 m0, s33
	v_lshl_add_u64 v[170:171], v[170:171], 0, v[146:147]
	global_load_lds_dwordx4 v[172:173], off
	s_add_i32 m0, s33, 0x2000
	s_nop 0
	global_load_lds_dwordx4 v[170:171], off
	s_waitcnt vmcnt(6)
	s_barrier
	v_mfma_f32_16x16x32_bf16 v[30:33], v[222:225], v[186:189], v[30:33]
	v_mfma_f32_16x16x32_bf16 v[26:29], v[232:235], v[186:189], v[26:29]
	v_mfma_f32_16x16x32_bf16 v[22:25], v[222:225], v[194:197], v[22:25]
	v_mfma_f32_16x16x32_bf16 v[18:21], v[232:235], v[194:197], v[18:21]
	v_mfma_f32_16x16x32_bf16 v[14:17], v[222:225], v[202:205], v[14:17]
	v_mfma_f32_16x16x32_bf16 v[10:13], v[232:235], v[202:205], v[10:13]
	v_mfma_f32_16x16x32_bf16 v[6:9], v[222:225], v[214:217], v[6:9]
	v_mfma_f32_16x16x32_bf16 v[2:5], v[232:235], v[214:217], v[2:5]
	v_mfma_f32_16x16x32_bf16 v[30:33], v[228:231], v[190:193], v[30:33]
	v_mfma_f32_16x16x32_bf16 v[26:29], v[236:239], v[190:193], v[26:29]
	v_mfma_f32_16x16x32_bf16 v[22:25], v[228:231], v[198:201], v[22:25]
	v_mfma_f32_16x16x32_bf16 v[18:21], v[236:239], v[198:201], v[18:21]
	v_mfma_f32_16x16x32_bf16 v[14:17], v[228:231], v[210:213], v[14:17]
	v_mfma_f32_16x16x32_bf16 v[10:13], v[236:239], v[210:213], v[10:13]
	v_mfma_f32_16x16x32_bf16 v[6:9], v[228:231], v[218:221], v[6:9]
	v_mfma_f32_16x16x32_bf16 v[2:5], v[236:239], v[218:221], v[2:5]
	s_barrier
	s_add_i32 s33, 0, 0x18000
	v_add_u32_e32 v169, s33, v167
	ds_read_b128 v[170:173], v169
	ds_read_b128 v[174:177], v169 offset:1024
	ds_read_b128 v[178:181], v169 offset:2048
	ds_read_b128 v[182:185], v169 offset:3072
	v_lshl_add_u64 v[206:207], v[206:207], 0, s[8:9]
	s_mov_b32 m0, s27
	v_lshl_add_u64 v[222:223], v[206:207], 0, v[138:139]
	ds_read_b128 v[186:189], v168 offset:32768
	ds_read_b128 v[190:193], v168 offset:33792
	ds_read_b128 v[194:197], v168 offset:34816
	ds_read_b128 v[198:201], v168 offset:35840
	ds_read_b128 v[202:205], v168 offset:36864
	ds_read_b128 v[210:213], v168 offset:37888
	ds_read_b128 v[214:217], v168 offset:38912
	ds_read_b128 v[218:221], v168 offset:39936
	global_load_lds_dwordx4 v[222:223], off
	v_lshl_add_u64 v[206:207], v[206:207], 0, v[146:147]
	s_mov_b32 m0, s28
	s_nop 0
	global_load_lds_dwordx4 v[206:207], off
	s_waitcnt lgkmcnt(8)
	s_barrier
	s_waitcnt lgkmcnt(7)
	v_mfma_f32_16x16x32_bf16 v[126:129], v[170:173], v[186:189], v[126:129]
	v_mfma_f32_16x16x32_bf16 v[122:125], v[178:181], v[186:189], v[122:125]
	s_waitcnt lgkmcnt(5)
	v_mfma_f32_16x16x32_bf16 v[118:121], v[170:173], v[194:197], v[118:121]
	v_mfma_f32_16x16x32_bf16 v[114:117], v[178:181], v[194:197], v[114:117]
	s_waitcnt lgkmcnt(3)
	v_mfma_f32_16x16x32_bf16 v[110:113], v[170:173], v[202:205], v[110:113]
	v_mfma_f32_16x16x32_bf16 v[106:109], v[178:181], v[202:205], v[106:109]
	s_waitcnt lgkmcnt(1)
	v_mfma_f32_16x16x32_bf16 v[102:105], v[170:173], v[214:217], v[102:105]
	v_mfma_f32_16x16x32_bf16 v[98:101], v[178:181], v[214:217], v[98:101]
	v_mfma_f32_16x16x32_bf16 v[126:129], v[174:177], v[190:193], v[126:129]
	v_mfma_f32_16x16x32_bf16 v[122:125], v[182:185], v[190:193], v[122:125]
	v_mfma_f32_16x16x32_bf16 v[118:121], v[174:177], v[198:201], v[118:121]
	v_mfma_f32_16x16x32_bf16 v[114:117], v[182:185], v[198:201], v[114:117]
	v_mfma_f32_16x16x32_bf16 v[110:113], v[174:177], v[210:213], v[110:113]
	v_mfma_f32_16x16x32_bf16 v[106:109], v[182:185], v[210:213], v[106:109]
	s_waitcnt lgkmcnt(0)
	v_mfma_f32_16x16x32_bf16 v[102:105], v[174:177], v[218:221], v[102:105]
	v_mfma_f32_16x16x32_bf16 v[98:101], v[182:185], v[218:221], v[98:101]
	s_barrier
	s_add_i32 s34, 0, 0x1c000
	s_add_i32 s33, s33, s25
	v_add_u32_e32 v169, s34, v167
	v_lshl_add_u64 v[206:207], v[240:241], 0, s[10:11]
	s_mov_b32 m0, s33
	ds_read_b128 v[222:225], v169
	ds_read_b128 v[228:231], v169 offset:1024
	ds_read_b128 v[232:235], v169 offset:2048
	ds_read_b128 v[236:239], v169 offset:3072
	global_load_lds_dwordx4 v[206:207], off
	v_lshl_add_u64 v[206:207], v[242:243], 0, s[10:11]
	s_add_i32 m0, s33, 0x2000
	s_nop 0
	global_load_lds_dwordx4 v[206:207], off
	s_barrier
	s_waitcnt lgkmcnt(3)
	v_mfma_f32_16x16x32_bf16 v[94:97], v[222:225], v[186:189], v[94:97]
	s_waitcnt lgkmcnt(1)
	v_mfma_f32_16x16x32_bf16 v[90:93], v[232:235], v[186:189], v[90:93]
	v_mfma_f32_16x16x32_bf16 v[86:89], v[222:225], v[194:197], v[86:89]
	v_mfma_f32_16x16x32_bf16 v[82:85], v[232:235], v[194:197], v[82:85]
	v_mfma_f32_16x16x32_bf16 v[78:81], v[222:225], v[202:205], v[78:81]
	v_mfma_f32_16x16x32_bf16 v[74:77], v[232:235], v[202:205], v[74:77]
	v_mfma_f32_16x16x32_bf16 v[70:73], v[222:225], v[214:217], v[70:73]
	v_mfma_f32_16x16x32_bf16 v[66:69], v[232:235], v[214:217], v[66:69]
	v_mfma_f32_16x16x32_bf16 v[94:97], v[228:231], v[190:193], v[94:97]
	s_waitcnt lgkmcnt(0)
	v_mfma_f32_16x16x32_bf16 v[90:93], v[236:239], v[190:193], v[90:93]
	v_mfma_f32_16x16x32_bf16 v[86:89], v[228:231], v[198:201], v[86:89]
	v_mfma_f32_16x16x32_bf16 v[82:85], v[236:239], v[198:201], v[82:85]
	v_mfma_f32_16x16x32_bf16 v[78:81], v[228:231], v[210:213], v[78:81]
	v_mfma_f32_16x16x32_bf16 v[74:77], v[236:239], v[210:213], v[74:77]
	v_mfma_f32_16x16x32_bf16 v[70:73], v[228:231], v[218:221], v[70:73]
	v_mfma_f32_16x16x32_bf16 v[66:69], v[236:239], v[218:221], v[66:69]
	s_barrier
	s_mov_b32 m0, s29
	v_lshl_add_u64 v[206:207], v[244:245], 0, s[10:11]
	ds_read_b128 v[186:189], v168 offset:49152
	ds_read_b128 v[190:193], v168 offset:50176
	ds_read_b128 v[194:197], v168 offset:51200
	ds_read_b128 v[198:201], v168 offset:52224
	ds_read_b128 v[202:205], v168 offset:53248
	ds_read_b128 v[210:213], v168 offset:54272
	ds_read_b128 v[214:217], v168 offset:55296
	ds_read_b128 v[218:221], v168 offset:56320
	global_load_lds_dwordx4 v[206:207], off
	v_lshl_add_u64 v[206:207], v[246:247], 0, s[10:11]
	s_mov_b32 m0, s30
	s_nop 0
	global_load_lds_dwordx4 v[206:207], off
	s_barrier
	s_waitcnt lgkmcnt(7)
	v_mfma_f32_16x16x32_bf16 v[62:65], v[170:173], v[186:189], v[62:65]
	v_mfma_f32_16x16x32_bf16 v[58:61], v[178:181], v[186:189], v[58:61]
	s_waitcnt lgkmcnt(5)
	v_mfma_f32_16x16x32_bf16 v[54:57], v[170:173], v[194:197], v[54:57]
	v_mfma_f32_16x16x32_bf16 v[50:53], v[178:181], v[194:197], v[50:53]
	s_waitcnt lgkmcnt(3)
	v_mfma_f32_16x16x32_bf16 v[46:49], v[170:173], v[202:205], v[46:49]
	v_mfma_f32_16x16x32_bf16 v[42:45], v[178:181], v[202:205], v[42:45]
	s_waitcnt lgkmcnt(1)
	v_mfma_f32_16x16x32_bf16 v[38:41], v[170:173], v[214:217], v[38:41]
	v_mfma_f32_16x16x32_bf16 v[34:37], v[178:181], v[214:217], v[34:37]
	v_mfma_f32_16x16x32_bf16 v[62:65], v[174:177], v[190:193], v[62:65]
	v_mfma_f32_16x16x32_bf16 v[58:61], v[182:185], v[190:193], v[58:61]
	v_mfma_f32_16x16x32_bf16 v[54:57], v[174:177], v[198:201], v[54:57]
	v_mfma_f32_16x16x32_bf16 v[50:53], v[182:185], v[198:201], v[50:53]
	v_mfma_f32_16x16x32_bf16 v[46:49], v[174:177], v[210:213], v[46:49]
	v_mfma_f32_16x16x32_bf16 v[42:45], v[182:185], v[210:213], v[42:45]
	s_waitcnt lgkmcnt(0)
	v_mfma_f32_16x16x32_bf16 v[38:41], v[174:177], v[218:221], v[38:41]
	v_mfma_f32_16x16x32_bf16 v[34:37], v[182:185], v[218:221], v[34:37]
	s_barrier
	v_lshl_add_u64 v[164:165], v[164:165], 0, s[12:13]
	s_add_i32 s33, s34, s25
	v_lshl_add_u64 v[170:171], v[164:165], 0, v[138:139]
	s_mov_b32 m0, s33
	v_lshl_add_u64 v[164:165], v[164:165], 0, v[146:147]
	global_load_lds_dwordx4 v[170:171], off
	s_add_i32 m0, s33, 0x2000
	s_nop 0
	global_load_lds_dwordx4 v[164:165], off
	s_waitcnt vmcnt(6)
	s_barrier
	v_mfma_f32_16x16x32_bf16 v[30:33], v[222:225], v[186:189], v[30:33]
	v_mfma_f32_16x16x32_bf16 v[26:29], v[232:235], v[186:189], v[26:29]
	v_mfma_f32_16x16x32_bf16 v[22:25], v[222:225], v[194:197], v[22:25]
	v_mfma_f32_16x16x32_bf16 v[18:21], v[232:235], v[194:197], v[18:21]
	v_mfma_f32_16x16x32_bf16 v[14:17], v[222:225], v[202:205], v[14:17]
	v_mfma_f32_16x16x32_bf16 v[10:13], v[232:235], v[202:205], v[10:13]
	v_mfma_f32_16x16x32_bf16 v[6:9], v[222:225], v[214:217], v[6:9]
	v_mfma_f32_16x16x32_bf16 v[2:5], v[232:235], v[214:217], v[2:5]
	v_mfma_f32_16x16x32_bf16 v[30:33], v[228:231], v[190:193], v[30:33]
	v_mfma_f32_16x16x32_bf16 v[26:29], v[236:239], v[190:193], v[26:29]
	v_mfma_f32_16x16x32_bf16 v[22:25], v[228:231], v[198:201], v[22:25]
	v_mfma_f32_16x16x32_bf16 v[18:21], v[236:239], v[198:201], v[18:21]
	v_mfma_f32_16x16x32_bf16 v[14:17], v[228:231], v[210:213], v[14:17]
	v_mfma_f32_16x16x32_bf16 v[10:13], v[236:239], v[210:213], v[10:13]
	v_mfma_f32_16x16x32_bf16 v[6:9], v[228:231], v[218:221], v[6:9]
	v_mfma_f32_16x16x32_bf16 v[2:5], v[236:239], v[218:221], v[2:5]
	s_barrier
	s_add_i32 s31, s31, 2
	s_add_u32 s6, s6, 0x100
	s_addc_u32 s7, s7, 0
	s_cmp_lt_u32 s31, 14
	s_cbranch_scc1 .LBB0_1645
	s_setprio 0
	s_waitcnt vmcnt(0)
	s_cmpk_gt_u32 s24, 0xff
	s_cbranch_scc1 .LBB0_1648
	s_barrier

.Lkprio_6:
.LBB0_1788:
	s_cmpk_eq_i32 s4, 0x700
	v_lshl_add_u64 v[170:171], v[162:163], 0, s[4:5]
	v_lshl_add_u64 v[170:171], v[170:171], 0, s[22:23]
	s_cselect_b64 vcc, -1, 0
	s_add_i32 s7, 0, 0x10000
	v_cndmask_b32_e32 v245, v171, v153, vcc
	v_add_u32_e32 v171, s7, v173
	ds_read_b128 v[176:179], v171
	ds_read_b128 v[180:183], v171 offset:1024
	ds_read_b128 v[184:187], v171 offset:2048
	ds_read_b128 v[188:191], v171 offset:3072
	v_cndmask_b32_e32 v244, v170, v152, vcc
	v_lshl_add_u64 v[170:171], v[168:169], 0, s[4:5]
	v_cndmask_b32_e32 v171, v171, v151, vcc
	v_cndmask_b32_e32 v170, v170, v150, vcc
	v_lshl_add_u64 v[228:229], v[164:165], 0, s[4:5]
	s_add_i32 m0, s34, 0xc000
	ds_read_b128 v[192:195], v174
	ds_read_b128 v[196:199], v174 offset:1024
	ds_read_b128 v[200:203], v174 offset:2048
	ds_read_b128 v[204:207], v174 offset:3072
	ds_read_b128 v[210:213], v174 offset:4096
	ds_read_b128 v[214:217], v174 offset:5120
	ds_read_b128 v[218:221], v174 offset:6144
	ds_read_b128 v[222:225], v174 offset:7168
	global_load_lds_dwordx4 v[228:229], off
	v_lshl_add_u64 v[228:229], v[166:167], 0, s[4:5]
	s_add_i32 m0, s34, 0xe000
	s_nop 0
	global_load_lds_dwordx4 v[228:229], off
	s_waitcnt lgkmcnt(8)
	s_barrier
	s_waitcnt lgkmcnt(7)
	v_mfma_f32_16x16x32_bf16 v[126:129], v[176:179], v[192:195], v[126:129]
	v_mfma_f32_16x16x32_bf16 v[122:125], v[184:187], v[192:195], v[122:125]
	s_waitcnt lgkmcnt(5)
	v_mfma_f32_16x16x32_bf16 v[118:121], v[176:179], v[200:203], v[118:121]
	v_mfma_f32_16x16x32_bf16 v[114:117], v[184:187], v[200:203], v[114:117]
	s_waitcnt lgkmcnt(3)
	v_mfma_f32_16x16x32_bf16 v[110:113], v[176:179], v[210:213], v[110:113]
	v_mfma_f32_16x16x32_bf16 v[106:109], v[184:187], v[210:213], v[106:109]
	s_waitcnt lgkmcnt(1)
	v_mfma_f32_16x16x32_bf16 v[102:105], v[176:179], v[218:221], v[102:105]
	v_mfma_f32_16x16x32_bf16 v[98:101], v[184:187], v[218:221], v[98:101]
	v_mfma_f32_16x16x32_bf16 v[126:129], v[180:183], v[196:199], v[126:129]
	v_mfma_f32_16x16x32_bf16 v[122:125], v[188:191], v[196:199], v[122:125]
	v_mfma_f32_16x16x32_bf16 v[118:121], v[180:183], v[204:207], v[118:121]
	v_mfma_f32_16x16x32_bf16 v[114:117], v[188:191], v[204:207], v[114:117]
	v_mfma_f32_16x16x32_bf16 v[110:113], v[180:183], v[214:217], v[110:113]
	v_mfma_f32_16x16x32_bf16 v[106:109], v[188:191], v[214:217], v[106:109]
	s_waitcnt lgkmcnt(0)
	v_mfma_f32_16x16x32_bf16 v[102:105], v[180:183], v[222:225], v[102:105]
	v_mfma_f32_16x16x32_bf16 v[98:101], v[188:191], v[222:225], v[98:101]
	s_barrier
	s_add_i32 s57, 0, 0x14000
	s_add_i32 s7, s7, s39
	v_add_u32_e32 v175, s57, v173
	v_lshl_add_u64 v[246:247], v[170:171], 0, v[138:139]
	s_mov_b32 m0, s7
	ds_read_b128 v[228:231], v175
	ds_read_b128 v[232:235], v175 offset:1024
	ds_read_b128 v[236:239], v175 offset:2048
	ds_read_b128 v[240:243], v175 offset:3072
	global_load_lds_dwordx4 v[246:247], off
	v_lshl_add_u64 v[248:249], v[170:171], 0, v[148:149]
	s_add_i32 m0, s7, 0x2000
	s_nop 0
	global_load_lds_dwordx4 v[248:249], off
	s_barrier
	s_waitcnt lgkmcnt(3)
	v_mfma_f32_16x16x32_bf16 v[94:97], v[228:231], v[192:195], v[94:97]
	s_waitcnt lgkmcnt(1)
	v_mfma_f32_16x16x32_bf16 v[90:93], v[236:239], v[192:195], v[90:93]
	v_mfma_f32_16x16x32_bf16 v[86:89], v[228:231], v[200:203], v[86:89]
	v_mfma_f32_16x16x32_bf16 v[82:85], v[236:239], v[200:203], v[82:85]
	v_mfma_f32_16x16x32_bf16 v[78:81], v[228:231], v[210:213], v[78:81]
	v_mfma_f32_16x16x32_bf16 v[74:77], v[236:239], v[210:213], v[74:77]
	v_mfma_f32_16x16x32_bf16 v[70:73], v[228:231], v[218:221], v[70:73]
	v_mfma_f32_16x16x32_bf16 v[66:69], v[236:239], v[218:221], v[66:69]
	v_mfma_f32_16x16x32_bf16 v[94:97], v[232:235], v[196:199], v[94:97]
	s_waitcnt lgkmcnt(0)
	v_mfma_f32_16x16x32_bf16 v[90:93], v[240:243], v[196:199], v[90:93]
	v_mfma_f32_16x16x32_bf16 v[86:89], v[232:235], v[204:207], v[86:89]
	v_mfma_f32_16x16x32_bf16 v[82:85], v[240:243], v[204:207], v[82:85]
	v_mfma_f32_16x16x32_bf16 v[78:81], v[232:235], v[214:217], v[78:81]
	v_mfma_f32_16x16x32_bf16 v[74:77], v[240:243], v[214:217], v[74:77]
	v_mfma_f32_16x16x32_bf16 v[70:73], v[232:235], v[222:225], v[70:73]
	v_mfma_f32_16x16x32_bf16 v[66:69], v[240:243], v[222:225], v[66:69]
	s_barrier
	s_mov_b32 m0, s34
	v_lshl_add_u64 v[250:251], v[244:245], 0, v[138:139]
	ds_read_b128 v[192:195], v174 offset:16384
	ds_read_b128 v[196:199], v174 offset:17408
	ds_read_b128 v[200:203], v174 offset:18432
	ds_read_b128 v[204:207], v174 offset:19456
	ds_read_b128 v[210:213], v174 offset:20480
	ds_read_b128 v[214:217], v174 offset:21504
	ds_read_b128 v[218:221], v174 offset:22528
	ds_read_b128 v[222:225], v174 offset:23552
	global_load_lds_dwordx4 v[250:251], off
	v_lshl_add_u64 v[252:253], v[244:245], 0, v[148:149]
	s_mov_b32 m0, s41
	s_nop 0
	global_load_lds_dwordx4 v[252:253], off
	s_barrier
	s_waitcnt lgkmcnt(7)
	v_mfma_f32_16x16x32_bf16 v[62:65], v[176:179], v[192:195], v[62:65]
	v_mfma_f32_16x16x32_bf16 v[58:61], v[184:187], v[192:195], v[58:61]
	s_waitcnt lgkmcnt(5)
	v_mfma_f32_16x16x32_bf16 v[54:57], v[176:179], v[200:203], v[54:57]
	v_mfma_f32_16x16x32_bf16 v[50:53], v[184:187], v[200:203], v[50:53]
	s_waitcnt lgkmcnt(3)
	v_mfma_f32_16x16x32_bf16 v[46:49], v[176:179], v[210:213], v[46:49]
	v_mfma_f32_16x16x32_bf16 v[42:45], v[184:187], v[210:213], v[42:45]
	s_waitcnt lgkmcnt(1)
	v_mfma_f32_16x16x32_bf16 v[38:41], v[176:179], v[218:221], v[38:41]
	v_mfma_f32_16x16x32_bf16 v[34:37], v[184:187], v[218:221], v[34:37]
	v_mfma_f32_16x16x32_bf16 v[62:65], v[180:183], v[196:199], v[62:65]
	v_mfma_f32_16x16x32_bf16 v[58:61], v[188:191], v[196:199], v[58:61]
	v_mfma_f32_16x16x32_bf16 v[54:57], v[180:183], v[204:207], v[54:57]
	v_mfma_f32_16x16x32_bf16 v[50:53], v[188:191], v[204:207], v[50:53]
	v_mfma_f32_16x16x32_bf16 v[46:49], v[180:183], v[214:217], v[46:49]
	v_mfma_f32_16x16x32_bf16 v[42:45], v[188:191], v[214:217], v[42:45]
	s_waitcnt lgkmcnt(0)
	v_mfma_f32_16x16x32_bf16 v[38:41], v[180:183], v[222:225], v[38:41]
	v_mfma_f32_16x16x32_bf16 v[34:37], v[188:191], v[222:225], v[34:37]
	s_barrier
	v_lshl_add_u64 v[176:177], v[170:171], 0, s[16:17]
	s_add_i32 s7, s57, s39
	v_lshl_add_u64 v[178:179], v[176:177], 0, v[138:139]
	s_mov_b32 m0, s7
	v_lshl_add_u64 v[176:177], v[176:177], 0, v[148:149]
	global_load_lds_dwordx4 v[178:179], off
	s_add_i32 m0, s7, 0x2000
	s_nop 0
	global_load_lds_dwordx4 v[176:177], off
	s_waitcnt vmcnt(6)
	s_barrier
	v_mfma_f32_16x16x32_bf16 v[30:33], v[228:231], v[192:195], v[30:33]
	v_mfma_f32_16x16x32_bf16 v[26:29], v[236:239], v[192:195], v[26:29]
	v_mfma_f32_16x16x32_bf16 v[22:25], v[228:231], v[200:203], v[22:25]
	v_mfma_f32_16x16x32_bf16 v[18:21], v[236:239], v[200:203], v[18:21]
	v_mfma_f32_16x16x32_bf16 v[14:17], v[228:231], v[210:213], v[14:17]
	v_mfma_f32_16x16x32_bf16 v[10:13], v[236:239], v[210:213], v[10:13]
	v_mfma_f32_16x16x32_bf16 v[6:9], v[228:231], v[218:221], v[6:9]
	v_mfma_f32_16x16x32_bf16 v[2:5], v[236:239], v[218:221], v[2:5]
	v_mfma_f32_16x16x32_bf16 v[30:33], v[232:235], v[196:199], v[30:33]
	v_mfma_f32_16x16x32_bf16 v[26:29], v[240:243], v[196:199], v[26:29]
	v_mfma_f32_16x16x32_bf16 v[22:25], v[232:235], v[204:207], v[22:25]
	v_mfma_f32_16x16x32_bf16 v[18:21], v[240:243], v[204:207], v[18:21]
	v_mfma_f32_16x16x32_bf16 v[14:17], v[232:235], v[214:217], v[14:17]
	v_mfma_f32_16x16x32_bf16 v[10:13], v[240:243], v[214:217], v[10:13]
	v_mfma_f32_16x16x32_bf16 v[6:9], v[232:235], v[222:225], v[6:9]
	v_mfma_f32_16x16x32_bf16 v[2:5], v[240:243], v[222:225], v[2:5]
	s_barrier
	s_add_i32 s7, 0, 0x18000
	v_add_u32_e32 v175, s7, v173
	ds_read_b128 v[176:179], v175
	ds_read_b128 v[180:183], v175 offset:1024
	ds_read_b128 v[184:187], v175 offset:2048
	ds_read_b128 v[188:191], v175 offset:3072
	v_lshl_add_u64 v[228:229], v[244:245], 0, s[16:17]
	s_mov_b32 m0, s42
	v_lshl_add_u64 v[230:231], v[228:229], 0, v[138:139]
	ds_read_b128 v[192:195], v174 offset:32768
	ds_read_b128 v[196:199], v174 offset:33792
	ds_read_b128 v[200:203], v174 offset:34816
	ds_read_b128 v[204:207], v174 offset:35840
	ds_read_b128 v[210:213], v174 offset:36864
	ds_read_b128 v[214:217], v174 offset:37888
	ds_read_b128 v[218:221], v174 offset:38912
	ds_read_b128 v[222:225], v174 offset:39936
	global_load_lds_dwordx4 v[230:231], off
	v_lshl_add_u64 v[228:229], v[228:229], 0, v[148:149]
	s_mov_b32 m0, s43
	s_nop 0
	global_load_lds_dwordx4 v[228:229], off
	s_waitcnt lgkmcnt(8)
	s_barrier
	s_waitcnt lgkmcnt(7)
	v_mfma_f32_16x16x32_bf16 v[126:129], v[176:179], v[192:195], v[126:129]
	v_mfma_f32_16x16x32_bf16 v[122:125], v[184:187], v[192:195], v[122:125]
	s_waitcnt lgkmcnt(5)
	v_mfma_f32_16x16x32_bf16 v[118:121], v[176:179], v[200:203], v[118:121]
	v_mfma_f32_16x16x32_bf16 v[114:117], v[184:187], v[200:203], v[114:117]
	s_waitcnt lgkmcnt(3)
	v_mfma_f32_16x16x32_bf16 v[110:113], v[176:179], v[210:213], v[110:113]
	v_mfma_f32_16x16x32_bf16 v[106:109], v[184:187], v[210:213], v[106:109]
	s_waitcnt lgkmcnt(1)
	v_mfma_f32_16x16x32_bf16 v[102:105], v[176:179], v[218:221], v[102:105]
	v_mfma_f32_16x16x32_bf16 v[98:101], v[184:187], v[218:221], v[98:101]
	v_mfma_f32_16x16x32_bf16 v[126:129], v[180:183], v[196:199], v[126:129]
	v_mfma_f32_16x16x32_bf16 v[122:125], v[188:191], v[196:199], v[122:125]
	v_mfma_f32_16x16x32_bf16 v[118:121], v[180:183], v[204:207], v[118:121]
	v_mfma_f32_16x16x32_bf16 v[114:117], v[188:191], v[204:207], v[114:117]
	v_mfma_f32_16x16x32_bf16 v[110:113], v[180:183], v[214:217], v[110:113]
	v_mfma_f32_16x16x32_bf16 v[106:109], v[188:191], v[214:217], v[106:109]
	s_waitcnt lgkmcnt(0)
	v_mfma_f32_16x16x32_bf16 v[102:105], v[180:183], v[222:225], v[102:105]
	v_mfma_f32_16x16x32_bf16 v[98:101], v[188:191], v[222:225], v[98:101]
	s_barrier
	s_add_i32 s57, 0, 0x1c000
	s_add_i32 s7, s7, s39
	v_add_u32_e32 v175, s57, v173
	v_lshl_add_u64 v[244:245], v[246:247], 0, s[18:19]
	s_mov_b32 m0, s7
	ds_read_b128 v[228:231], v175
	ds_read_b128 v[232:235], v175 offset:1024
	ds_read_b128 v[236:239], v175 offset:2048
	ds_read_b128 v[240:243], v175 offset:3072
	global_load_lds_dwordx4 v[244:245], off
	v_lshl_add_u64 v[244:245], v[248:249], 0, s[18:19]
	s_add_i32 m0, s7, 0x2000
	s_nop 0
	global_load_lds_dwordx4 v[244:245], off
	s_barrier
	s_waitcnt lgkmcnt(3)
	v_mfma_f32_16x16x32_bf16 v[94:97], v[228:231], v[192:195], v[94:97]
	s_waitcnt lgkmcnt(1)
	v_mfma_f32_16x16x32_bf16 v[90:93], v[236:239], v[192:195], v[90:93]
	v_mfma_f32_16x16x32_bf16 v[86:89], v[228:231], v[200:203], v[86:89]
	v_mfma_f32_16x16x32_bf16 v[82:85], v[236:239], v[200:203], v[82:85]
	v_mfma_f32_16x16x32_bf16 v[78:81], v[228:231], v[210:213], v[78:81]
	v_mfma_f32_16x16x32_bf16 v[74:77], v[236:239], v[210:213], v[74:77]
	v_mfma_f32_16x16x32_bf16 v[70:73], v[228:231], v[218:221], v[70:73]
	v_mfma_f32_16x16x32_bf16 v[66:69], v[236:239], v[218:221], v[66:69]
	v_mfma_f32_16x16x32_bf16 v[94:97], v[232:235], v[196:199], v[94:97]
	s_waitcnt lgkmcnt(0)
	v_mfma_f32_16x16x32_bf16 v[90:93], v[240:243], v[196:199], v[90:93]
	v_mfma_f32_16x16x32_bf16 v[86:89], v[232:235], v[204:207], v[86:89]
	v_mfma_f32_16x16x32_bf16 v[82:85], v[240:243], v[204:207], v[82:85]
	v_mfma_f32_16x16x32_bf16 v[78:81], v[232:235], v[214:217], v[78:81]
	v_mfma_f32_16x16x32_bf16 v[74:77], v[240:243], v[214:217], v[74:77]
	v_mfma_f32_16x16x32_bf16 v[70:73], v[232:235], v[222:225], v[70:73]
	v_mfma_f32_16x16x32_bf16 v[66:69], v[240:243], v[222:225], v[66:69]
	s_barrier
	s_mov_b32 m0, s55
	v_lshl_add_u64 v[244:245], v[250:251], 0, s[18:19]
	ds_read_b128 v[192:195], v174 offset:49152
	ds_read_b128 v[196:199], v174 offset:50176
	ds_read_b128 v[200:203], v174 offset:51200
	ds_read_b128 v[204:207], v174 offset:52224
	ds_read_b128 v[210:213], v174 offset:53248
	ds_read_b128 v[214:217], v174 offset:54272
	ds_read_b128 v[218:221], v174 offset:55296
	ds_read_b128 v[222:225], v174 offset:56320
	global_load_lds_dwordx4 v[244:245], off
	v_lshl_add_u64 v[244:245], v[252:253], 0, s[18:19]
	s_mov_b32 m0, s56
	s_nop 0
	global_load_lds_dwordx4 v[244:245], off
	s_barrier
	s_waitcnt lgkmcnt(7)
	v_mfma_f32_16x16x32_bf16 v[62:65], v[176:179], v[192:195], v[62:65]
	v_mfma_f32_16x16x32_bf16 v[58:61], v[184:187], v[192:195], v[58:61]
	s_waitcnt lgkmcnt(5)
	v_mfma_f32_16x16x32_bf16 v[54:57], v[176:179], v[200:203], v[54:57]
	v_mfma_f32_16x16x32_bf16 v[50:53], v[184:187], v[200:203], v[50:53]
	s_waitcnt lgkmcnt(3)
	v_mfma_f32_16x16x32_bf16 v[46:49], v[176:179], v[210:213], v[46:49]
	v_mfma_f32_16x16x32_bf16 v[42:45], v[184:187], v[210:213], v[42:45]
	s_waitcnt lgkmcnt(1)
	v_mfma_f32_16x16x32_bf16 v[38:41], v[176:179], v[218:221], v[38:41]
	v_mfma_f32_16x16x32_bf16 v[34:37], v[184:187], v[218:221], v[34:37]
	v_mfma_f32_16x16x32_bf16 v[62:65], v[180:183], v[196:199], v[62:65]
	v_mfma_f32_16x16x32_bf16 v[58:61], v[188:191], v[196:199], v[58:61]
	v_mfma_f32_16x16x32_bf16 v[54:57], v[180:183], v[204:207], v[54:57]
	v_mfma_f32_16x16x32_bf16 v[50:53], v[188:191], v[204:207], v[50:53]
	v_mfma_f32_16x16x32_bf16 v[46:49], v[180:183], v[214:217], v[46:49]
	v_mfma_f32_16x16x32_bf16 v[42:45], v[188:191], v[214:217], v[42:45]
	s_waitcnt lgkmcnt(0)
	v_mfma_f32_16x16x32_bf16 v[38:41], v[180:183], v[222:225], v[38:41]
	v_mfma_f32_16x16x32_bf16 v[34:37], v[188:191], v[222:225], v[34:37]
	s_barrier
	v_lshl_add_u64 v[170:171], v[170:171], 0, s[20:21]
	s_add_i32 s7, s57, s39
	v_lshl_add_u64 v[176:177], v[170:171], 0, v[138:139]
	s_mov_b32 m0, s7
	v_lshl_add_u64 v[170:171], v[170:171], 0, v[148:149]
	global_load_lds_dwordx4 v[176:177], off
	s_add_i32 m0, s7, 0x2000
	s_nop 0
	global_load_lds_dwordx4 v[170:171], off
	s_waitcnt vmcnt(6)
	s_barrier
	v_mfma_f32_16x16x32_bf16 v[30:33], v[228:231], v[192:195], v[30:33]
	v_mfma_f32_16x16x32_bf16 v[26:29], v[236:239], v[192:195], v[26:29]
	v_mfma_f32_16x16x32_bf16 v[22:25], v[228:231], v[200:203], v[22:25]
	v_mfma_f32_16x16x32_bf16 v[18:21], v[236:239], v[200:203], v[18:21]
	v_mfma_f32_16x16x32_bf16 v[14:17], v[228:231], v[210:213], v[14:17]
	v_mfma_f32_16x16x32_bf16 v[10:13], v[236:239], v[210:213], v[10:13]
	v_mfma_f32_16x16x32_bf16 v[6:9], v[228:231], v[218:221], v[6:9]
	v_mfma_f32_16x16x32_bf16 v[2:5], v[236:239], v[218:221], v[2:5]
	v_mfma_f32_16x16x32_bf16 v[30:33], v[232:235], v[196:199], v[30:33]
	v_mfma_f32_16x16x32_bf16 v[26:29], v[240:243], v[196:199], v[26:29]
	v_mfma_f32_16x16x32_bf16 v[22:25], v[232:235], v[204:207], v[22:25]
	v_mfma_f32_16x16x32_bf16 v[18:21], v[240:243], v[204:207], v[18:21]
	v_mfma_f32_16x16x32_bf16 v[14:17], v[232:235], v[214:217], v[14:17]
	v_mfma_f32_16x16x32_bf16 v[10:13], v[240:243], v[214:217], v[10:13]
	v_mfma_f32_16x16x32_bf16 v[6:9], v[232:235], v[222:225], v[6:9]
	v_mfma_f32_16x16x32_bf16 v[2:5], v[240:243], v[222:225], v[2:5]
	s_barrier
	s_add_i32 s6, s6, 2
	s_add_u32 s4, s4, 0x100
	s_addc_u32 s5, s5, 0
	s_cmp_lt_u32 s6, 14
	s_cbranch_scc1 .LBB0_1788
	s_setprio 0
	s_waitcnt vmcnt(0)
	s_cmpk_gt_u32 s38, 0xff
	s_cbranch_scc1 .LBB0_1791
	s_barrier

.Lkprio_7:
.LBB0_1914:
	s_add_u32 s38, s4, 0xf8cd0080
	s_addc_u32 s39, s5, -1
	s_cmp_lg_u32 s37, 40
	s_cselect_b32 s39, s39, 0
	s_cselect_b32 s38, s38, 0
	s_add_i32 s40, 0, 0x10000
	v_add_u32_e32 v156, s40, v162
	ds_read_b128 v[164:167], v156
	ds_read_b128 v[168:171], v156 offset:1024
	ds_read_b128 v[172:175], v156 offset:2048
	ds_read_b128 v[176:179], v156 offset:3072
	v_lshl_add_u64 v[232:233], v[148:149], 0, s[38:39]
	v_lshl_add_u64 v[156:157], v[146:147], 0, s[38:39]
	v_lshl_add_u64 v[214:215], v[150:151], 0, s[4:5]
	s_add_i32 m0, s28, 0xc000
	ds_read_b128 v[180:183], v163
	ds_read_b128 v[184:187], v163 offset:1024
	ds_read_b128 v[188:191], v163 offset:2048
	ds_read_b128 v[192:195], v163 offset:3072
	ds_read_b128 v[196:199], v163 offset:4096
	ds_read_b128 v[200:203], v163 offset:5120
	ds_read_b128 v[204:207], v163 offset:6144
	ds_read_b128 v[210:213], v163 offset:7168
	global_load_lds_dwordx4 v[214:215], off
	v_lshl_add_u64 v[214:215], v[152:153], 0, s[4:5]
	s_add_i32 m0, s28, 0xe000
	s_nop 0
	global_load_lds_dwordx4 v[214:215], off
	s_waitcnt lgkmcnt(8)
	s_barrier
	s_waitcnt lgkmcnt(7)
	v_mfma_f32_16x16x32_bf16 v[126:129], v[164:167], v[180:183], v[126:129]
	v_mfma_f32_16x16x32_bf16 v[122:125], v[172:175], v[180:183], v[122:125]
	s_waitcnt lgkmcnt(5)
	v_mfma_f32_16x16x32_bf16 v[118:121], v[164:167], v[188:191], v[118:121]
	v_mfma_f32_16x16x32_bf16 v[114:117], v[172:175], v[188:191], v[114:117]
	s_waitcnt lgkmcnt(3)
	v_mfma_f32_16x16x32_bf16 v[110:113], v[164:167], v[196:199], v[110:113]
	v_mfma_f32_16x16x32_bf16 v[106:109], v[172:175], v[196:199], v[106:109]
	s_waitcnt lgkmcnt(1)
	v_mfma_f32_16x16x32_bf16 v[102:105], v[164:167], v[204:207], v[102:105]
	v_mfma_f32_16x16x32_bf16 v[98:101], v[172:175], v[204:207], v[98:101]
	v_mfma_f32_16x16x32_bf16 v[126:129], v[168:171], v[184:187], v[126:129]
	v_mfma_f32_16x16x32_bf16 v[122:125], v[176:179], v[184:187], v[122:125]
	v_mfma_f32_16x16x32_bf16 v[118:121], v[168:171], v[192:195], v[118:121]
	v_mfma_f32_16x16x32_bf16 v[114:117], v[176:179], v[192:195], v[114:117]
	v_mfma_f32_16x16x32_bf16 v[110:113], v[168:171], v[200:203], v[110:113]
	v_mfma_f32_16x16x32_bf16 v[106:109], v[176:179], v[200:203], v[106:109]
	s_waitcnt lgkmcnt(0)
	v_mfma_f32_16x16x32_bf16 v[102:105], v[168:171], v[210:213], v[102:105]
	v_mfma_f32_16x16x32_bf16 v[98:101], v[176:179], v[210:213], v[98:101]
	s_barrier
	s_add_i32 s38, 0, 0x14000
	s_add_i32 s39, s40, s27
	v_add_u32_e32 v208, s38, v162
	v_lshl_add_u64 v[234:235], v[156:157], 0, v[130:131]
	s_mov_b32 m0, s39
	ds_read_b128 v[214:217], v208
	ds_read_b128 v[218:221], v208 offset:1024
	ds_read_b128 v[222:225], v208 offset:2048
	ds_read_b128 v[228:231], v208 offset:3072
	global_load_lds_dwordx4 v[234:235], off
	v_lshl_add_u64 v[236:237], v[156:157], 0, v[144:145]
	s_add_i32 m0, s39, 0x2000
	s_nop 0
	global_load_lds_dwordx4 v[236:237], off
	s_barrier
	s_waitcnt lgkmcnt(3)
	v_mfma_f32_16x16x32_bf16 v[94:97], v[214:217], v[180:183], v[94:97]
	s_waitcnt lgkmcnt(1)
	v_mfma_f32_16x16x32_bf16 v[90:93], v[222:225], v[180:183], v[90:93]
	v_mfma_f32_16x16x32_bf16 v[86:89], v[214:217], v[188:191], v[86:89]
	v_mfma_f32_16x16x32_bf16 v[82:85], v[222:225], v[188:191], v[82:85]
	v_mfma_f32_16x16x32_bf16 v[78:81], v[214:217], v[196:199], v[78:81]
	v_mfma_f32_16x16x32_bf16 v[74:77], v[222:225], v[196:199], v[74:77]
	v_mfma_f32_16x16x32_bf16 v[70:73], v[214:217], v[204:207], v[70:73]
	v_mfma_f32_16x16x32_bf16 v[66:69], v[222:225], v[204:207], v[66:69]
	v_mfma_f32_16x16x32_bf16 v[94:97], v[218:221], v[184:187], v[94:97]
	s_waitcnt lgkmcnt(0)
	v_mfma_f32_16x16x32_bf16 v[90:93], v[228:231], v[184:187], v[90:93]
	v_mfma_f32_16x16x32_bf16 v[86:89], v[218:221], v[192:195], v[86:89]
	v_mfma_f32_16x16x32_bf16 v[82:85], v[228:231], v[192:195], v[82:85]
	v_mfma_f32_16x16x32_bf16 v[78:81], v[218:221], v[200:203], v[78:81]
	v_mfma_f32_16x16x32_bf16 v[74:77], v[228:231], v[200:203], v[74:77]
	v_mfma_f32_16x16x32_bf16 v[70:73], v[218:221], v[210:213], v[70:73]
	v_mfma_f32_16x16x32_bf16 v[66:69], v[228:231], v[210:213], v[66:69]
	s_barrier
	s_mov_b32 m0, s28
	v_lshl_add_u64 v[238:239], v[232:233], 0, v[130:131]
	ds_read_b128 v[180:183], v163 offset:16384
	ds_read_b128 v[184:187], v163 offset:17408
	ds_read_b128 v[188:191], v163 offset:18432
	ds_read_b128 v[192:195], v163 offset:19456
	ds_read_b128 v[196:199], v163 offset:20480
	ds_read_b128 v[200:203], v163 offset:21504
	ds_read_b128 v[204:207], v163 offset:22528
	ds_read_b128 v[210:213], v163 offset:23552
	global_load_lds_dwordx4 v[238:239], off
	v_lshl_add_u64 v[240:241], v[232:233], 0, v[144:145]
	s_mov_b32 m0, s29
	s_nop 0
	global_load_lds_dwordx4 v[240:241], off
	s_barrier
	s_waitcnt lgkmcnt(7)
	v_mfma_f32_16x16x32_bf16 v[62:65], v[164:167], v[180:183], v[62:65]
	v_mfma_f32_16x16x32_bf16 v[58:61], v[172:175], v[180:183], v[58:61]
	s_waitcnt lgkmcnt(5)
	v_mfma_f32_16x16x32_bf16 v[54:57], v[164:167], v[188:191], v[54:57]
	v_mfma_f32_16x16x32_bf16 v[50:53], v[172:175], v[188:191], v[50:53]
	s_waitcnt lgkmcnt(3)
	v_mfma_f32_16x16x32_bf16 v[46:49], v[164:167], v[196:199], v[46:49]
	v_mfma_f32_16x16x32_bf16 v[42:45], v[172:175], v[196:199], v[42:45]
	s_waitcnt lgkmcnt(1)
	v_mfma_f32_16x16x32_bf16 v[38:41], v[164:167], v[204:207], v[38:41]
	v_mfma_f32_16x16x32_bf16 v[34:37], v[172:175], v[204:207], v[34:37]
	v_mfma_f32_16x16x32_bf16 v[62:65], v[168:171], v[184:187], v[62:65]
	v_mfma_f32_16x16x32_bf16 v[58:61], v[176:179], v[184:187], v[58:61]
	v_mfma_f32_16x16x32_bf16 v[54:57], v[168:171], v[192:195], v[54:57]
	v_mfma_f32_16x16x32_bf16 v[50:53], v[176:179], v[192:195], v[50:53]
	v_mfma_f32_16x16x32_bf16 v[46:49], v[168:171], v[200:203], v[46:49]
	v_mfma_f32_16x16x32_bf16 v[42:45], v[176:179], v[200:203], v[42:45]
	s_waitcnt lgkmcnt(0)
	v_mfma_f32_16x16x32_bf16 v[38:41], v[168:171], v[210:213], v[38:41]
	v_mfma_f32_16x16x32_bf16 v[34:37], v[176:179], v[210:213], v[34:37]
	s_barrier
	v_lshl_add_u64 v[164:165], v[156:157], 0, s[16:17]
	s_add_i32 s38, s38, s27
	v_lshl_add_u64 v[166:167], v[164:165], 0, v[130:131]
	s_mov_b32 m0, s38
	v_lshl_add_u64 v[164:165], v[164:165], 0, v[144:145]
	global_load_lds_dwordx4 v[166:167], off
	s_add_i32 m0, s38, 0x2000
	s_nop 0
	global_load_lds_dwordx4 v[164:165], off
	s_waitcnt vmcnt(6)
	s_barrier
	v_mfma_f32_16x16x32_bf16 v[30:33], v[214:217], v[180:183], v[30:33]
	v_mfma_f32_16x16x32_bf16 v[26:29], v[222:225], v[180:183], v[26:29]
	v_mfma_f32_16x16x32_bf16 v[22:25], v[214:217], v[188:191], v[22:25]
	v_mfma_f32_16x16x32_bf16 v[18:21], v[222:225], v[188:191], v[18:21]
	v_mfma_f32_16x16x32_bf16 v[14:17], v[214:217], v[196:199], v[14:17]
	v_mfma_f32_16x16x32_bf16 v[10:13], v[222:225], v[196:199], v[10:13]
	v_mfma_f32_16x16x32_bf16 v[6:9], v[214:217], v[204:207], v[6:9]
	v_mfma_f32_16x16x32_bf16 v[2:5], v[222:225], v[204:207], v[2:5]
	v_mfma_f32_16x16x32_bf16 v[30:33], v[218:221], v[184:187], v[30:33]
	v_mfma_f32_16x16x32_bf16 v[26:29], v[228:231], v[184:187], v[26:29]
	v_mfma_f32_16x16x32_bf16 v[22:25], v[218:221], v[192:195], v[22:25]
	v_mfma_f32_16x16x32_bf16 v[18:21], v[228:231], v[192:195], v[18:21]
	v_mfma_f32_16x16x32_bf16 v[14:17], v[218:221], v[200:203], v[14:17]
	v_mfma_f32_16x16x32_bf16 v[10:13], v[228:231], v[200:203], v[10:13]
	v_mfma_f32_16x16x32_bf16 v[6:9], v[218:221], v[210:213], v[6:9]
	v_mfma_f32_16x16x32_bf16 v[2:5], v[228:231], v[210:213], v[2:5]
	s_barrier
	s_add_i32 s38, 0, 0x18000
	v_add_u32_e32 v176, s38, v162
	ds_read_b128 v[164:167], v176
	ds_read_b128 v[168:171], v176 offset:1024
	ds_read_b128 v[172:175], v176 offset:2048
	ds_read_b128 v[176:179], v176 offset:3072
	v_lshl_add_u64 v[214:215], v[232:233], 0, s[16:17]
	s_mov_b32 m0, s31
	v_lshl_add_u64 v[216:217], v[214:215], 0, v[130:131]
	ds_read_b128 v[180:183], v163 offset:32768
	ds_read_b128 v[184:187], v163 offset:33792
	ds_read_b128 v[188:191], v163 offset:34816
	ds_read_b128 v[192:195], v163 offset:35840
	ds_read_b128 v[196:199], v163 offset:36864
	ds_read_b128 v[200:203], v163 offset:37888
	ds_read_b128 v[204:207], v163 offset:38912
	ds_read_b128 v[210:213], v163 offset:39936
	global_load_lds_dwordx4 v[216:217], off
	v_lshl_add_u64 v[214:215], v[214:215], 0, v[144:145]
	s_mov_b32 m0, s34
	s_nop 0
	global_load_lds_dwordx4 v[214:215], off
	s_waitcnt lgkmcnt(8)
	s_barrier
	s_waitcnt lgkmcnt(7)
	v_mfma_f32_16x16x32_bf16 v[126:129], v[164:167], v[180:183], v[126:129]
	v_mfma_f32_16x16x32_bf16 v[122:125], v[172:175], v[180:183], v[122:125]
	s_waitcnt lgkmcnt(5)
	v_mfma_f32_16x16x32_bf16 v[118:121], v[164:167], v[188:191], v[118:121]
	v_mfma_f32_16x16x32_bf16 v[114:117], v[172:175], v[188:191], v[114:117]
	s_waitcnt lgkmcnt(3)
	v_mfma_f32_16x16x32_bf16 v[110:113], v[164:167], v[196:199], v[110:113]
	v_mfma_f32_16x16x32_bf16 v[106:109], v[172:175], v[196:199], v[106:109]
	s_waitcnt lgkmcnt(1)
	v_mfma_f32_16x16x32_bf16 v[102:105], v[164:167], v[204:207], v[102:105]
	v_mfma_f32_16x16x32_bf16 v[98:101], v[172:175], v[204:207], v[98:101]
	v_mfma_f32_16x16x32_bf16 v[126:129], v[168:171], v[184:187], v[126:129]
	v_mfma_f32_16x16x32_bf16 v[122:125], v[176:179], v[184:187], v[122:125]
	v_mfma_f32_16x16x32_bf16 v[118:121], v[168:171], v[192:195], v[118:121]
	v_mfma_f32_16x16x32_bf16 v[114:117], v[176:179], v[192:195], v[114:117]
	v_mfma_f32_16x16x32_bf16 v[110:113], v[168:171], v[200:203], v[110:113]
	v_mfma_f32_16x16x32_bf16 v[106:109], v[176:179], v[200:203], v[106:109]
	s_waitcnt lgkmcnt(0)
	v_mfma_f32_16x16x32_bf16 v[102:105], v[168:171], v[210:213], v[102:105]
	v_mfma_f32_16x16x32_bf16 v[98:101], v[176:179], v[210:213], v[98:101]
	s_barrier
	s_add_i32 s39, 0, 0x1c000
	s_add_i32 s38, s38, s27
	v_add_u32_e32 v208, s39, v162
	v_lshl_add_u64 v[232:233], v[234:235], 0, s[18:19]
	s_mov_b32 m0, s38
	ds_read_b128 v[214:217], v208
	ds_read_b128 v[218:221], v208 offset:1024
	ds_read_b128 v[222:225], v208 offset:2048
	ds_read_b128 v[228:231], v208 offset:3072
	global_load_lds_dwordx4 v[232:233], off
	v_lshl_add_u64 v[232:233], v[236:237], 0, s[18:19]
	s_add_i32 m0, s38, 0x2000
	s_nop 0
	global_load_lds_dwordx4 v[232:233], off
	s_barrier
	s_waitcnt lgkmcnt(3)
	v_mfma_f32_16x16x32_bf16 v[94:97], v[214:217], v[180:183], v[94:97]
	s_waitcnt lgkmcnt(1)
	v_mfma_f32_16x16x32_bf16 v[90:93], v[222:225], v[180:183], v[90:93]
	v_mfma_f32_16x16x32_bf16 v[86:89], v[214:217], v[188:191], v[86:89]
	v_mfma_f32_16x16x32_bf16 v[82:85], v[222:225], v[188:191], v[82:85]
	v_mfma_f32_16x16x32_bf16 v[78:81], v[214:217], v[196:199], v[78:81]
	v_mfma_f32_16x16x32_bf16 v[74:77], v[222:225], v[196:199], v[74:77]
	v_mfma_f32_16x16x32_bf16 v[70:73], v[214:217], v[204:207], v[70:73]
	v_mfma_f32_16x16x32_bf16 v[66:69], v[222:225], v[204:207], v[66:69]
	v_mfma_f32_16x16x32_bf16 v[94:97], v[218:221], v[184:187], v[94:97]
	s_waitcnt lgkmcnt(0)
	v_mfma_f32_16x16x32_bf16 v[90:93], v[228:231], v[184:187], v[90:93]
	v_mfma_f32_16x16x32_bf16 v[86:89], v[218:221], v[192:195], v[86:89]
	v_mfma_f32_16x16x32_bf16 v[82:85], v[228:231], v[192:195], v[82:85]
	v_mfma_f32_16x16x32_bf16 v[78:81], v[218:221], v[200:203], v[78:81]
	v_mfma_f32_16x16x32_bf16 v[74:77], v[228:231], v[200:203], v[74:77]
	v_mfma_f32_16x16x32_bf16 v[70:73], v[218:221], v[210:213], v[70:73]
	v_mfma_f32_16x16x32_bf16 v[66:69], v[228:231], v[210:213], v[66:69]
	s_barrier
	s_mov_b32 m0, s35
	v_lshl_add_u64 v[232:233], v[238:239], 0, s[18:19]
	ds_read_b128 v[180:183], v163 offset:49152
	ds_read_b128 v[184:187], v163 offset:50176
	ds_read_b128 v[188:191], v163 offset:51200
	ds_read_b128 v[192:195], v163 offset:52224
	ds_read_b128 v[196:199], v163 offset:53248
	ds_read_b128 v[200:203], v163 offset:54272
	ds_read_b128 v[204:207], v163 offset:55296
	ds_read_b128 v[210:213], v163 offset:56320
	global_load_lds_dwordx4 v[232:233], off
	v_lshl_add_u64 v[232:233], v[240:241], 0, s[18:19]
	s_mov_b32 m0, s36
	s_nop 0
	global_load_lds_dwordx4 v[232:233], off
	s_barrier
	s_waitcnt lgkmcnt(7)
	v_mfma_f32_16x16x32_bf16 v[62:65], v[164:167], v[180:183], v[62:65]
	v_mfma_f32_16x16x32_bf16 v[58:61], v[172:175], v[180:183], v[58:61]
	s_waitcnt lgkmcnt(5)
	v_mfma_f32_16x16x32_bf16 v[54:57], v[164:167], v[188:191], v[54:57]
	v_mfma_f32_16x16x32_bf16 v[50:53], v[172:175], v[188:191], v[50:53]
	s_waitcnt lgkmcnt(3)
	v_mfma_f32_16x16x32_bf16 v[46:49], v[164:167], v[196:199], v[46:49]
	v_mfma_f32_16x16x32_bf16 v[42:45], v[172:175], v[196:199], v[42:45]
	s_waitcnt lgkmcnt(1)
	v_mfma_f32_16x16x32_bf16 v[38:41], v[164:167], v[204:207], v[38:41]
	v_mfma_f32_16x16x32_bf16 v[34:37], v[172:175], v[204:207], v[34:37]
	v_mfma_f32_16x16x32_bf16 v[62:65], v[168:171], v[184:187], v[62:65]
	v_mfma_f32_16x16x32_bf16 v[58:61], v[176:179], v[184:187], v[58:61]
	v_mfma_f32_16x16x32_bf16 v[54:57], v[168:171], v[192:195], v[54:57]
	v_mfma_f32_16x16x32_bf16 v[50:53], v[176:179], v[192:195], v[50:53]
	v_mfma_f32_16x16x32_bf16 v[46:49], v[168:171], v[200:203], v[46:49]
	v_mfma_f32_16x16x32_bf16 v[42:45], v[176:179], v[200:203], v[42:45]
	s_waitcnt lgkmcnt(0)
	v_mfma_f32_16x16x32_bf16 v[38:41], v[168:171], v[210:213], v[38:41]
	v_mfma_f32_16x16x32_bf16 v[34:37], v[176:179], v[210:213], v[34:37]
	s_barrier
	v_lshl_add_u64 v[156:157], v[156:157], 0, s[20:21]
	s_add_i32 s38, s39, s27
	v_lshl_add_u64 v[164:165], v[156:157], 0, v[130:131]
	s_mov_b32 m0, s38
	v_lshl_add_u64 v[156:157], v[156:157], 0, v[144:145]
	global_load_lds_dwordx4 v[164:165], off
	s_add_i32 m0, s38, 0x2000
	s_nop 0
	global_load_lds_dwordx4 v[156:157], off
	s_waitcnt vmcnt(6)
	s_barrier
	v_mfma_f32_16x16x32_bf16 v[30:33], v[214:217], v[180:183], v[30:33]
	v_mfma_f32_16x16x32_bf16 v[26:29], v[222:225], v[180:183], v[26:29]
	v_mfma_f32_16x16x32_bf16 v[22:25], v[214:217], v[188:191], v[22:25]
	v_mfma_f32_16x16x32_bf16 v[18:21], v[222:225], v[188:191], v[18:21]
	v_mfma_f32_16x16x32_bf16 v[14:17], v[214:217], v[196:199], v[14:17]
	v_mfma_f32_16x16x32_bf16 v[10:13], v[222:225], v[196:199], v[10:13]
	v_mfma_f32_16x16x32_bf16 v[6:9], v[214:217], v[204:207], v[6:9]
	v_mfma_f32_16x16x32_bf16 v[2:5], v[222:225], v[204:207], v[2:5]
	v_mfma_f32_16x16x32_bf16 v[30:33], v[218:221], v[184:187], v[30:33]
	v_mfma_f32_16x16x32_bf16 v[26:29], v[228:231], v[184:187], v[26:29]
	v_mfma_f32_16x16x32_bf16 v[22:25], v[218:221], v[192:195], v[22:25]
	v_mfma_f32_16x16x32_bf16 v[18:21], v[228:231], v[192:195], v[18:21]
	v_mfma_f32_16x16x32_bf16 v[14:17], v[218:221], v[200:203], v[14:17]
	v_mfma_f32_16x16x32_bf16 v[10:13], v[228:231], v[200:203], v[10:13]
	v_mfma_f32_16x16x32_bf16 v[6:9], v[218:221], v[210:213], v[6:9]
	v_mfma_f32_16x16x32_bf16 v[2:5], v[228:231], v[210:213], v[2:5]
	s_barrier
	s_add_i32 s37, s37, 2
	s_add_u32 s4, s4, 0x100
	s_addc_u32 s5, s5, 0
	s_cmp_lt_u32 s37, 42
	s_cbranch_scc1 .LBB0_1914
	s_setprio 0
	s_waitcnt vmcnt(0)
	s_cmpk_gt_u32 s26, 0xff
	s_cbranch_scc1 .LBB0_1917
	s_barrier
